# A/B: GEMM K-loops with the LOADER wave at s_setprio 1 during its load segments (inverse of the original flips)
# speedup vs baseline: 1.0065x; 1.0005x over previous
; #define PG8_STAGE(bufoff, gbase, voff) do { _Pragma("unroll") for (int _i = 0; _i < 2; ++_i) \
;         __builtin_amdgcn_global_load_lds((const unsigned*)((const char*)(gbase) + (voff)[_i]), (PG8_LAS unsigned*)(lds + (bufoff) + ldsw + _i * 8192), 16, 0, 0); } while (0)
; #define PG8_LDA(dst, b, h) do { _Pragma("unroll") for (int m = 0; m < 4; ++m) _Pragma("unroll") for (int k = 0; k < 2; ++k) dst[m][k] = *(const PG8_LAS bf16x8*)(lds + PG8_SA(b, h) + aoff + m * 2048 + k * 1024); } while (0)
; #define PG8_LDB(dst, b, h) do { _Pragma("unroll") for (int n = 0; n < 2; ++n) _Pragma("unroll") for (int k = 0; k < 2; ++k) dst[n][k] = *(const PG8_LAS bf16x8*)(lds + PG8_SB(b, h) + boff + n * 2048 + k * 1024); } while (0)
; #define PG8_MMA(ai, bj, At, Bt) do { __builtin_amdgcn_s_setprio(1); _Pragma("unroll") for (int m = 0; m < 4; ++m) _Pragma("unroll") for (int n = 0; n < 2; ++n) _Pragma("unroll") for (int k = 0; k < 2; ++k) \
;         acc[ai][bj][m][n] = __builtin_amdgcn_mfma_f32_16x16x32_bf16(Bt[n][k], At[m][k], acc[ai][bj][m][n], 0, 0, 0); __builtin_amdgcn_s_setprio(0); } while (0)
; #define PG8_WAIT_V(n) asm volatile("s_waitcnt vmcnt(" #n ")" ::: "memory")
; #define PG8_WAIT_L(n) asm volatile("s_waitcnt lgkmcnt(" #n ")" ::: "memory")
; #define PG8_BAR __builtin_amdgcn_s_barrier()
; template <class Epi, class Sched, bool ALIGN_EPI = false, bool SP2 = false>
; __device__ __forceinline__ void gemm_phase(PG8_LAS unsigned char* lds, const Gemm g, const Sched& S, const Epi& E) {
;     ...
;             const char* a1 = cA + (size_t)(t + 1) * kstep;
;             const char* a2 = last ? nA : cA + (size_t)(t + 2) * kstep; const char* b2 = last ? nB : cB + (size_t)(t + 2) * kstep;
;             const char* a3 = a2 + kstep; const char* b3 = b2 + kstep;
;             if (last && has_next) S.a_ready(nxt);
;             if constexpr (SP2) {
;             PG8_LDB(B0, 0, 0); PG8_LDB(B1, 0, 1); PG8_SCHED; PG8_LDA(At, 0, 0); PG8_STAGE(PG8_SA(1, 1), a1 + hstep, voffA);
;             PG8_WAIT_V(8); PG8_WAIT_L(0); PG8_BAR; PG8_MMA(0, 0, At, B0); PG8_MMA(0, 1, At, B1); PG8_BAR; PG8_SCHED;
;             PG8_LDA(At, 0, 1); PG8_STAGE(PG8_SB(0, 0), b2, voffB); PG8_STAGE(PG8_SB(0, 1), b2 + hstep, voffB); PG8_STAGE(PG8_SA(0, 0), a2, voffA);
;             PG8_WAIT_V(8); PG8_WAIT_L(0); PG8_BAR; PG8_MMA(1, 0, At, B0); PG8_MMA(1, 1, At, B1); PG8_BAR; PG8_SCHED;
.LBB0_25:
	s_setprio 1
	s_add_i32 s88, 0, 0x10000
	s_add_i32 s90, 0, 0x14000
	ds_read_b128 v[142:145], v200
	ds_read_b128 v[146:149], v200 offset:1024
	ds_read_b128 v[150:153], v200 offset:2048
	ds_read_b128 v[154:157], v200 offset:3072
	ds_read_b128 v[164:167], v200 offset:16384
	ds_read_b128 v[168:171], v200 offset:17408
	ds_read_b128 v[172:175], v200 offset:18432
	ds_read_b128 v[176:179], v200 offset:19456
	s_add_i32 m0, s29, 0xc000
	ds_read_b128 v[180:183], v141
	ds_read_b128 v[184:187], v141 offset:1024
	ds_read_b128 v[188:191], v141 offset:2048
	ds_read_b128 v[192:195], v141 offset:3072
	ds_read_b128 v[196:199], v141 offset:4096
	ds_read_b128 v[222:225], v141 offset:5120
	ds_read_b128 v[226:229], v141 offset:6144
	ds_read_b128 v[230:233], v141 offset:7168
	global_load_lds_dwordx4 v134, s[80:81]
	s_add_i32 m0, s29, 0xe000
	s_nop 0
	global_load_lds_dwordx4 v136, s[80:81]
	s_add_u32 s4, s80, 0xfff80080
	s_addc_u32 s5, s81, -1
	s_cmp_eq_u32 s87, 28
	s_cselect_b32 s53, s55, s5
	s_cselect_b32 s52, s83, s4
	s_cselect_b32 s5, s73, s86
	s_cselect_b32 s4, s84, s85
	s_waitcnt vmcnt(8)
	s_waitcnt lgkmcnt(0)
	s_setprio 0
	s_barrier
	s_waitcnt lgkmcnt(0)
	v_mfma_f32_16x16x32_bf16 v[124:127], v[142:145], v[180:183], v[124:127]
	v_mfma_f32_16x16x32_bf16 v[120:123], v[150:153], v[180:183], v[120:123]
	v_mfma_f32_16x16x32_bf16 v[116:119], v[142:145], v[188:191], v[116:119]
	v_mfma_f32_16x16x32_bf16 v[112:115], v[150:153], v[188:191], v[112:115]
	v_mfma_f32_16x16x32_bf16 v[100:103], v[142:145], v[196:199], v[100:103]
	v_mfma_f32_16x16x32_bf16 v[96:99], v[150:153], v[196:199], v[96:99]
	v_mfma_f32_16x16x32_bf16 v[84:87], v[142:145], v[226:229], v[84:87]
	v_mfma_f32_16x16x32_bf16 v[80:83], v[150:153], v[226:229], v[80:83]
	v_mfma_f32_16x16x32_bf16 v[124:127], v[146:149], v[184:187], v[124:127]
	v_mfma_f32_16x16x32_bf16 v[120:123], v[154:157], v[184:187], v[120:123]
	v_mfma_f32_16x16x32_bf16 v[116:119], v[146:149], v[192:195], v[116:119]
	v_mfma_f32_16x16x32_bf16 v[112:115], v[154:157], v[192:195], v[112:115]
	v_mfma_f32_16x16x32_bf16 v[100:103], v[146:149], v[222:225], v[100:103]
	v_mfma_f32_16x16x32_bf16 v[96:99], v[154:157], v[222:225], v[96:99]
	v_mfma_f32_16x16x32_bf16 v[84:87], v[146:149], v[230:233], v[84:87]
	v_mfma_f32_16x16x32_bf16 v[80:83], v[154:157], v[230:233], v[80:83]
	v_mfma_f32_16x16x32_bf16 v[108:111], v[164:167], v[180:183], v[108:111]
	v_mfma_f32_16x16x32_bf16 v[104:107], v[172:175], v[180:183], v[104:107]
	v_mfma_f32_16x16x32_bf16 v[92:95], v[164:167], v[188:191], v[92:95]
	v_mfma_f32_16x16x32_bf16 v[88:91], v[172:175], v[188:191], v[88:91]
	v_mfma_f32_16x16x32_bf16 v[76:79], v[164:167], v[196:199], v[76:79]
	v_mfma_f32_16x16x32_bf16 v[72:75], v[172:175], v[196:199], v[72:75]
	v_mfma_f32_16x16x32_bf16 v[68:71], v[164:167], v[226:229], v[68:71]
	v_mfma_f32_16x16x32_bf16 v[64:67], v[172:175], v[226:229], v[64:67]
	v_mfma_f32_16x16x32_bf16 v[108:111], v[168:171], v[184:187], v[108:111]
	v_mfma_f32_16x16x32_bf16 v[104:107], v[176:179], v[184:187], v[104:107]
	v_mfma_f32_16x16x32_bf16 v[92:95], v[168:171], v[192:195], v[92:95]
	v_mfma_f32_16x16x32_bf16 v[88:91], v[176:179], v[192:195], v[88:91]
	v_mfma_f32_16x16x32_bf16 v[76:79], v[168:171], v[222:225], v[76:79]
	v_mfma_f32_16x16x32_bf16 v[72:75], v[176:179], v[222:225], v[72:75]
	v_mfma_f32_16x16x32_bf16 v[68:71], v[168:171], v[230:233], v[68:71]
	v_mfma_f32_16x16x32_bf16 v[64:67], v[176:179], v[230:233], v[64:67]
	s_barrier
	s_setprio 1
	s_add_i32 s88, s88, s28
	s_mov_b32 m0, s88
	ds_read_b128 v[180:183], v141 offset:16384
	ds_read_b128 v[184:187], v141 offset:17408
	ds_read_b128 v[188:191], v141 offset:18432
	ds_read_b128 v[192:195], v141 offset:19456
	ds_read_b128 v[196:199], v141 offset:20480
	ds_read_b128 v[222:225], v141 offset:21504
	ds_read_b128 v[226:229], v141 offset:22528
	ds_read_b128 v[230:233], v141 offset:23552
	global_load_lds_dwordx4 v160, s[4:5]
	s_add_i32 m0, s88, 0x2000
	s_add_u32 s88, s4, 0x80000
	s_addc_u32 s89, s5, 0
	s_add_i32 s90, s90, s28
	global_load_lds_dwordx4 v128, s[4:5]
	s_mov_b32 m0, s90
	s_nop 0
	global_load_lds_dwordx4 v160, s[88:89]
	s_add_i32 m0, s90, 0x2000
	s_nop 0
	global_load_lds_dwordx4 v128, s[88:89]
	s_mov_b32 m0, s29
	s_nop 0
	global_load_lds_dwordx4 v132, s[52:53]
	s_mov_b32 m0, s45
	s_nop 0
	global_load_lds_dwordx4 v130, s[52:53]
	s_add_u32 s98, s52, 0x80
	s_addc_u32 s99, s53, 0
	s_waitcnt vmcnt(8)
	s_waitcnt lgkmcnt(0)
	s_setprio 0
	s_barrier
	s_waitcnt lgkmcnt(0)
	v_mfma_f32_16x16x32_bf16 v[60:63], v[142:145], v[180:183], v[60:63]
	v_mfma_f32_16x16x32_bf16 v[56:59], v[150:153], v[180:183], v[56:59]
	v_mfma_f32_16x16x32_bf16 v[52:55], v[142:145], v[188:191], v[52:55]
	v_mfma_f32_16x16x32_bf16 v[48:51], v[150:153], v[188:191], v[48:51]
	v_mfma_f32_16x16x32_bf16 v[36:39], v[142:145], v[196:199], v[36:39]
	v_mfma_f32_16x16x32_bf16 v[32:35], v[150:153], v[196:199], v[32:35]
	v_mfma_f32_16x16x32_bf16 v[20:23], v[142:145], v[226:229], v[20:23]
	v_mfma_f32_16x16x32_bf16 v[16:19], v[150:153], v[226:229], v[16:19]
	v_mfma_f32_16x16x32_bf16 v[60:63], v[146:149], v[184:187], v[60:63]
	v_mfma_f32_16x16x32_bf16 v[56:59], v[154:157], v[184:187], v[56:59]
	v_mfma_f32_16x16x32_bf16 v[52:55], v[146:149], v[192:195], v[52:55]
	v_mfma_f32_16x16x32_bf16 v[48:51], v[154:157], v[192:195], v[48:51]
	v_mfma_f32_16x16x32_bf16 v[36:39], v[146:149], v[222:225], v[36:39]
	v_mfma_f32_16x16x32_bf16 v[32:35], v[154:157], v[222:225], v[32:35]
	v_mfma_f32_16x16x32_bf16 v[20:23], v[146:149], v[230:233], v[20:23]
	v_mfma_f32_16x16x32_bf16 v[16:19], v[154:157], v[230:233], v[16:19]
	v_mfma_f32_16x16x32_bf16 v[44:47], v[164:167], v[180:183], v[44:47]
	v_mfma_f32_16x16x32_bf16 v[40:43], v[172:175], v[180:183], v[40:43]
	v_mfma_f32_16x16x32_bf16 v[28:31], v[164:167], v[188:191], v[28:31]
	v_mfma_f32_16x16x32_bf16 v[24:27], v[172:175], v[188:191], v[24:27]
	v_mfma_f32_16x16x32_bf16 v[12:15], v[164:167], v[196:199], v[12:15]
	v_mfma_f32_16x16x32_bf16 v[8:11], v[172:175], v[196:199], v[8:11]
	v_mfma_f32_16x16x32_bf16 v[4:7], v[164:167], v[226:229], v[4:7]
	v_mfma_f32_16x16x32_bf16 v[0:3], v[172:175], v[226:229], v[0:3]
	v_mfma_f32_16x16x32_bf16 v[44:47], v[168:171], v[184:187], v[44:47]
	v_mfma_f32_16x16x32_bf16 v[40:43], v[176:179], v[184:187], v[40:43]
	v_mfma_f32_16x16x32_bf16 v[28:31], v[168:171], v[192:195], v[28:31]
	v_mfma_f32_16x16x32_bf16 v[24:27], v[176:179], v[192:195], v[24:27]
	v_mfma_f32_16x16x32_bf16 v[12:15], v[168:171], v[222:225], v[12:15]
	v_mfma_f32_16x16x32_bf16 v[8:11], v[176:179], v[222:225], v[8:11]
	v_mfma_f32_16x16x32_bf16 v[4:7], v[168:171], v[230:233], v[4:7]
	v_mfma_f32_16x16x32_bf16 v[0:3], v[176:179], v[230:233], v[0:3]
	s_barrier
; #define PG8_STAGE(bufoff, gbase, voff) do { _Pragma("unroll") for (int _i = 0; _i < 2; ++_i) \
;         __builtin_amdgcn_global_load_lds((const unsigned*)((const char*)(gbase) + (voff)[_i]), (PG8_LAS unsigned*)(lds + (bufoff) + ldsw + _i * 8192), 16, 0, 0); } while (0)
; #define PG8_LDA(dst, b, h) do { _Pragma("unroll") for (int m = 0; m < 4; ++m) _Pragma("unroll") for (int k = 0; k < 2; ++k) dst[m][k] = *(const PG8_LAS bf16x8*)(lds + PG8_SA(b, h) + aoff + m * 2048 + k * 1024); } while (0)
; #define PG8_LDB(dst, b, h) do { _Pragma("unroll") for (int n = 0; n < 2; ++n) _Pragma("unroll") for (int k = 0; k < 2; ++k) dst[n][k] = *(const PG8_LAS bf16x8*)(lds + PG8_SB(b, h) + boff + n * 2048 + k * 1024); } while (0)
; #define PG8_MMA(ai, bj, At, Bt) do { __builtin_amdgcn_s_setprio(1); _Pragma("unroll") for (int m = 0; m < 4; ++m) _Pragma("unroll") for (int n = 0; n < 2; ++n) _Pragma("unroll") for (int k = 0; k < 2; ++k) \
;         acc[ai][bj][m][n] = __builtin_amdgcn_mfma_f32_16x16x32_bf16(Bt[n][k], At[m][k], acc[ai][bj][m][n], 0, 0, 0); __builtin_amdgcn_s_setprio(0); } while (0)
; #define PG8_WAIT_V(n) asm volatile("s_waitcnt vmcnt(" #n ")" ::: "memory")
; #define PG8_WAIT_L(n) asm volatile("s_waitcnt lgkmcnt(" #n ")" ::: "memory")
; #define PG8_BAR __builtin_amdgcn_s_barrier()
; #define PG8_SCHED __builtin_amdgcn_sched_barrier(0)
; template <class Epi, class Sched, bool ALIGN_EPI = false, bool SP2 = false>
; __device__ __forceinline__ void gemm_phase(PG8_LAS unsigned char* lds, const Gemm g, const Sched& S, const Epi& E) {
;     ...
;             PG8_LDB(B0, 1, 0); PG8_LDB(B1, 1, 1); PG8_SCHED; PG8_LDA(At, 1, 0); PG8_STAGE(PG8_SA(0, 1), a2 + hstep, voffA);
;             PG8_WAIT_V(8); PG8_WAIT_L(0); PG8_BAR; PG8_MMA(0, 0, At, B0); PG8_MMA(0, 1, At, B1); PG8_BAR; PG8_SCHED;
;             PG8_LDA(At, 1, 1); PG8_STAGE(PG8_SB(1, 0), b3, voffB); PG8_STAGE(PG8_SB(1, 1), b3 + hstep, voffB); PG8_STAGE(PG8_SA(1, 0), a3, voffA);
;             PG8_WAIT_V(8); PG8_WAIT_L(0); PG8_BAR; PG8_MMA(1, 0, At, B0); PG8_MMA(1, 1, At, B1); PG8_BAR; PG8_SCHED;
	s_setprio 1
	s_add_i32 s88, 0, 0x18000
	s_add_i32 s89, 0, 0x1c000
	ds_read_b128 v[142:145], v200 offset:32768
	ds_read_b128 v[146:149], v200 offset:33792
	ds_read_b128 v[150:153], v200 offset:34816
	ds_read_b128 v[154:157], v200 offset:35840
	ds_read_b128 v[164:167], v200 offset:49152
	ds_read_b128 v[168:171], v200 offset:50176
	ds_read_b128 v[172:175], v200 offset:51200
	ds_read_b128 v[176:179], v200 offset:52224
	s_add_u32 s52, s52, 0x80000
	s_addc_u32 s53, s53, 0
	s_mov_b32 m0, s56
	ds_read_b128 v[180:183], v141 offset:32768
	ds_read_b128 v[184:187], v141 offset:33792
	ds_read_b128 v[188:191], v141 offset:34816
	ds_read_b128 v[192:195], v141 offset:35840
	ds_read_b128 v[196:199], v141 offset:36864
	ds_read_b128 v[222:225], v141 offset:37888
	ds_read_b128 v[226:229], v141 offset:38912
	ds_read_b128 v[230:233], v141 offset:39936
	global_load_lds_dwordx4 v132, s[52:53]
	s_mov_b32 m0, s57
	s_nop 0
	global_load_lds_dwordx4 v130, s[52:53]
	s_waitcnt vmcnt(8)
	s_waitcnt lgkmcnt(0)
	s_setprio 0
	s_barrier
	s_waitcnt lgkmcnt(0)
	v_mfma_f32_16x16x32_bf16 v[124:127], v[142:145], v[180:183], v[124:127]
	v_mfma_f32_16x16x32_bf16 v[120:123], v[150:153], v[180:183], v[120:123]
	v_mfma_f32_16x16x32_bf16 v[116:119], v[142:145], v[188:191], v[116:119]
	v_mfma_f32_16x16x32_bf16 v[112:115], v[150:153], v[188:191], v[112:115]
	v_mfma_f32_16x16x32_bf16 v[100:103], v[142:145], v[196:199], v[100:103]
	v_mfma_f32_16x16x32_bf16 v[96:99], v[150:153], v[196:199], v[96:99]
	v_mfma_f32_16x16x32_bf16 v[84:87], v[142:145], v[226:229], v[84:87]
	v_mfma_f32_16x16x32_bf16 v[80:83], v[150:153], v[226:229], v[80:83]
	v_mfma_f32_16x16x32_bf16 v[124:127], v[146:149], v[184:187], v[124:127]
	v_mfma_f32_16x16x32_bf16 v[120:123], v[154:157], v[184:187], v[120:123]
	v_mfma_f32_16x16x32_bf16 v[116:119], v[146:149], v[192:195], v[116:119]
	v_mfma_f32_16x16x32_bf16 v[112:115], v[154:157], v[192:195], v[112:115]
	v_mfma_f32_16x16x32_bf16 v[100:103], v[146:149], v[222:225], v[100:103]
	v_mfma_f32_16x16x32_bf16 v[96:99], v[154:157], v[222:225], v[96:99]
	v_mfma_f32_16x16x32_bf16 v[84:87], v[146:149], v[230:233], v[84:87]
	v_mfma_f32_16x16x32_bf16 v[80:83], v[154:157], v[230:233], v[80:83]
	v_mfma_f32_16x16x32_bf16 v[108:111], v[164:167], v[180:183], v[108:111]
	v_mfma_f32_16x16x32_bf16 v[104:107], v[172:175], v[180:183], v[104:107]
	v_mfma_f32_16x16x32_bf16 v[92:95], v[164:167], v[188:191], v[92:95]
	v_mfma_f32_16x16x32_bf16 v[88:91], v[172:175], v[188:191], v[88:91]
	v_mfma_f32_16x16x32_bf16 v[76:79], v[164:167], v[196:199], v[76:79]
	v_mfma_f32_16x16x32_bf16 v[72:75], v[172:175], v[196:199], v[72:75]
	v_mfma_f32_16x16x32_bf16 v[68:71], v[164:167], v[226:229], v[68:71]
	v_mfma_f32_16x16x32_bf16 v[64:67], v[172:175], v[226:229], v[64:67]
	v_mfma_f32_16x16x32_bf16 v[108:111], v[168:171], v[184:187], v[108:111]
	v_mfma_f32_16x16x32_bf16 v[104:107], v[176:179], v[184:187], v[104:107]
	v_mfma_f32_16x16x32_bf16 v[92:95], v[168:171], v[192:195], v[92:95]
	v_mfma_f32_16x16x32_bf16 v[88:91], v[176:179], v[192:195], v[88:91]
	v_mfma_f32_16x16x32_bf16 v[76:79], v[168:171], v[222:225], v[76:79]
	v_mfma_f32_16x16x32_bf16 v[72:75], v[176:179], v[222:225], v[72:75]
	v_mfma_f32_16x16x32_bf16 v[68:71], v[168:171], v[230:233], v[68:71]
	v_mfma_f32_16x16x32_bf16 v[64:67], v[176:179], v[230:233], v[64:67]
	s_barrier
	s_setprio 1
	s_add_i32 s52, s88, s28
	s_mov_b32 m0, s52
	ds_read_b128 v[180:183], v141 offset:49152
	ds_read_b128 v[184:187], v141 offset:50176
	ds_read_b128 v[188:191], v141 offset:51200
	ds_read_b128 v[192:195], v141 offset:52224
	ds_read_b128 v[196:199], v141 offset:53248
	ds_read_b128 v[222:225], v141 offset:54272
	ds_read_b128 v[226:229], v141 offset:55296
	ds_read_b128 v[230:233], v141 offset:56320
	s_add_u32 s4, s4, 0x80
	s_addc_u32 s5, s5, 0
	global_load_lds_dwordx4 v160, s[4:5]
	s_add_i32 m0, s52, 0x2000
	s_add_i32 s52, s89, s28
	global_load_lds_dwordx4 v128, s[4:5]
	s_add_u32 s4, s4, 0x80000
	s_addc_u32 s5, s5, 0
	s_mov_b32 m0, s52
	s_nop 0
	global_load_lds_dwordx4 v160, s[4:5]
	s_add_i32 m0, s52, 0x2000
	s_nop 0
	global_load_lds_dwordx4 v128, s[4:5]
	s_mov_b32 m0, s24
	s_nop 0
	global_load_lds_dwordx4 v132, s[98:99]
	s_mov_b32 m0, s59
	s_nop 0
	global_load_lds_dwordx4 v130, s[98:99]
	s_waitcnt vmcnt(8)
	s_waitcnt lgkmcnt(0)
	s_setprio 0
	s_barrier
	s_waitcnt lgkmcnt(0)
	v_mfma_f32_16x16x32_bf16 v[60:63], v[142:145], v[180:183], v[60:63]
	v_mfma_f32_16x16x32_bf16 v[56:59], v[150:153], v[180:183], v[56:59]
	v_mfma_f32_16x16x32_bf16 v[52:55], v[142:145], v[188:191], v[52:55]
	v_mfma_f32_16x16x32_bf16 v[48:51], v[150:153], v[188:191], v[48:51]
	v_mfma_f32_16x16x32_bf16 v[36:39], v[142:145], v[196:199], v[36:39]
	v_mfma_f32_16x16x32_bf16 v[32:35], v[150:153], v[196:199], v[32:35]
	v_mfma_f32_16x16x32_bf16 v[20:23], v[142:145], v[226:229], v[20:23]
	v_mfma_f32_16x16x32_bf16 v[16:19], v[150:153], v[226:229], v[16:19]
	v_mfma_f32_16x16x32_bf16 v[60:63], v[146:149], v[184:187], v[60:63]
	v_mfma_f32_16x16x32_bf16 v[56:59], v[154:157], v[184:187], v[56:59]
	v_mfma_f32_16x16x32_bf16 v[52:55], v[146:149], v[192:195], v[52:55]
	v_mfma_f32_16x16x32_bf16 v[48:51], v[154:157], v[192:195], v[48:51]
	v_mfma_f32_16x16x32_bf16 v[36:39], v[146:149], v[222:225], v[36:39]
	v_mfma_f32_16x16x32_bf16 v[32:35], v[154:157], v[222:225], v[32:35]
	v_mfma_f32_16x16x32_bf16 v[20:23], v[146:149], v[230:233], v[20:23]
	v_mfma_f32_16x16x32_bf16 v[16:19], v[154:157], v[230:233], v[16:19]
	v_mfma_f32_16x16x32_bf16 v[44:47], v[164:167], v[180:183], v[44:47]
	v_mfma_f32_16x16x32_bf16 v[40:43], v[172:175], v[180:183], v[40:43]
	v_mfma_f32_16x16x32_bf16 v[28:31], v[164:167], v[188:191], v[28:31]
	v_mfma_f32_16x16x32_bf16 v[24:27], v[172:175], v[188:191], v[24:27]
	v_mfma_f32_16x16x32_bf16 v[12:15], v[164:167], v[196:199], v[12:15]
	v_mfma_f32_16x16x32_bf16 v[8:11], v[172:175], v[196:199], v[8:11]
	v_mfma_f32_16x16x32_bf16 v[4:7], v[164:167], v[226:229], v[4:7]
	v_mfma_f32_16x16x32_bf16 v[0:3], v[172:175], v[226:229], v[0:3]
	v_mfma_f32_16x16x32_bf16 v[44:47], v[168:171], v[184:187], v[44:47]
	v_mfma_f32_16x16x32_bf16 v[40:43], v[176:179], v[184:187], v[40:43]
	v_mfma_f32_16x16x32_bf16 v[28:31], v[168:171], v[192:195], v[28:31]
	v_mfma_f32_16x16x32_bf16 v[24:27], v[176:179], v[192:195], v[24:27]
	v_mfma_f32_16x16x32_bf16 v[12:15], v[168:171], v[222:225], v[12:15]
	v_mfma_f32_16x16x32_bf16 v[8:11], v[176:179], v[222:225], v[8:11]
	v_mfma_f32_16x16x32_bf16 v[4:7], v[168:171], v[230:233], v[4:7]
	v_mfma_f32_16x16x32_bf16 v[0:3], v[176:179], v[230:233], v[0:3]
	s_barrier
	s_add_i32 s87, s87, 2
	s_add_u32 s80, s80, 0x100
	s_addc_u32 s81, s81, 0
	s_add_u32 s85, s85, 0x100
	s_addc_u32 s86, s86, 0
	s_cmp_gt_u32 s87, 29
	s_cbranch_scc0 .LBB0_25
	s_and_b64 vcc, exec, s[42:43]
	s_cbranch_vccz .LBB0_28
	s_barrier

; #define PG8_STAGE(bufoff, gbase, voff) do { _Pragma("unroll") for (int _i = 0; _i < 2; ++_i) \
;         __builtin_amdgcn_global_load_lds((const unsigned*)((const char*)(gbase) + (voff)[_i]), (PG8_LAS unsigned*)(lds + (bufoff) + ldsw + _i * 8192), 16, 0, 0); } while (0)
; #define PG8_LDA(dst, b, h) do { _Pragma("unroll") for (int m = 0; m < 4; ++m) _Pragma("unroll") for (int k = 0; k < 2; ++k) dst[m][k] = *(const PG8_LAS bf16x8*)(lds + PG8_SA(b, h) + aoff + m * 2048 + k * 1024); } while (0)
; #define PG8_LDB(dst, b, h) do { _Pragma("unroll") for (int n = 0; n < 2; ++n) _Pragma("unroll") for (int k = 0; k < 2; ++k) dst[n][k] = *(const PG8_LAS bf16x8*)(lds + PG8_SB(b, h) + boff + n * 2048 + k * 1024); } while (0)
; #define PG8_MMA(ai, bj, At, Bt) do { __builtin_amdgcn_s_setprio(1); _Pragma("unroll") for (int m = 0; m < 4; ++m) _Pragma("unroll") for (int n = 0; n < 2; ++n) _Pragma("unroll") for (int k = 0; k < 2; ++k) \
;         acc[ai][bj][m][n] = __builtin_amdgcn_mfma_f32_16x16x32_bf16(Bt[n][k], At[m][k], acc[ai][bj][m][n], 0, 0, 0); __builtin_amdgcn_s_setprio(0); } while (0)
; #define PG8_WAIT_V(n) asm volatile("s_waitcnt vmcnt(" #n ")" ::: "memory")
; #define PG8_WAIT_L(n) asm volatile("s_waitcnt lgkmcnt(" #n ")" ::: "memory")
; #define PG8_BAR __builtin_amdgcn_s_barrier()
; template <class Epi, class Sched, bool ALIGN_EPI = false, bool SP2 = false>
; __device__ __forceinline__ void gemm_phase(PG8_LAS unsigned char* lds, const Gemm g, const Sched& S, const Epi& E) {
;     ...
;             const char* a1 = cA + (size_t)(t + 1) * kstep;
;             const char* a2 = last ? nA : cA + (size_t)(t + 2) * kstep; const char* b2 = last ? nB : cB + (size_t)(t + 2) * kstep;
;             const char* a3 = a2 + kstep; const char* b3 = b2 + kstep;
;             if (last && has_next) S.a_ready(nxt);
;             if constexpr (SP2) {
;             PG8_LDB(B0, 0, 0); PG8_LDB(B1, 0, 1); PG8_SCHED; PG8_LDA(At, 0, 0); PG8_STAGE(PG8_SA(1, 1), a1 + hstep, voffA);
;             PG8_WAIT_V(8); PG8_WAIT_L(0); PG8_BAR; PG8_MMA(0, 0, At, B0); PG8_MMA(0, 1, At, B1); PG8_BAR; PG8_SCHED;
;             PG8_LDA(At, 0, 1); PG8_STAGE(PG8_SB(0, 0), b2, voffB); PG8_STAGE(PG8_SB(0, 1), b2 + hstep, voffB); PG8_STAGE(PG8_SA(0, 0), a2, voffA);
;             PG8_WAIT_V(8); PG8_WAIT_L(0); PG8_BAR; PG8_MMA(1, 0, At, B0); PG8_MMA(1, 1, At, B1); PG8_BAR; PG8_SCHED;
.LBB0_52:
	s_setprio 1
	s_add_i32 s84, 0, 0x10000
	s_add_i32 s85, 0, 0x14000
	ds_read_b128 v[142:145], v200
	ds_read_b128 v[146:149], v200 offset:1024
	ds_read_b128 v[150:153], v200 offset:2048
	ds_read_b128 v[154:157], v200 offset:3072
	ds_read_b128 v[164:167], v200 offset:16384
	ds_read_b128 v[168:171], v200 offset:17408
	ds_read_b128 v[172:175], v200 offset:18432
	ds_read_b128 v[176:179], v200 offset:19456
	s_add_i32 m0, s28, 0xc000
	ds_read_b128 v[180:183], v141
	ds_read_b128 v[184:187], v141 offset:1024
	ds_read_b128 v[188:191], v141 offset:2048
	ds_read_b128 v[192:195], v141 offset:3072
	ds_read_b128 v[196:199], v141 offset:4096
	ds_read_b128 v[222:225], v141 offset:5120
	ds_read_b128 v[226:229], v141 offset:6144
	ds_read_b128 v[230:233], v141 offset:7168
	global_load_lds_dwordx4 v134, s[72:73]
	s_add_i32 m0, s28, 0xe000
	s_nop 0
	global_load_lds_dwordx4 v136, s[72:73]
	s_add_u32 s4, s72, 0x100
	s_addc_u32 s5, s73, 0
	s_cmpk_eq_i32 s83, 0x54
	s_cselect_b32 s57, s45, s5
	s_cselect_b32 s56, s44, s4
	s_cselect_b32 s53, s55, s82
	s_cselect_b32 s52, s54, s81
	s_waitcnt vmcnt(8)
	s_waitcnt lgkmcnt(0)
	s_setprio 0
	s_barrier
	s_waitcnt lgkmcnt(0)
	v_mfma_f32_16x16x32_bf16 v[124:127], v[142:145], v[180:183], v[124:127]
	v_mfma_f32_16x16x32_bf16 v[120:123], v[150:153], v[180:183], v[120:123]
	v_mfma_f32_16x16x32_bf16 v[116:119], v[142:145], v[188:191], v[116:119]
	v_mfma_f32_16x16x32_bf16 v[112:115], v[150:153], v[188:191], v[112:115]
	v_mfma_f32_16x16x32_bf16 v[100:103], v[142:145], v[196:199], v[100:103]
	v_mfma_f32_16x16x32_bf16 v[96:99], v[150:153], v[196:199], v[96:99]
	v_mfma_f32_16x16x32_bf16 v[84:87], v[142:145], v[226:229], v[84:87]
	v_mfma_f32_16x16x32_bf16 v[80:83], v[150:153], v[226:229], v[80:83]
	v_mfma_f32_16x16x32_bf16 v[124:127], v[146:149], v[184:187], v[124:127]
	v_mfma_f32_16x16x32_bf16 v[120:123], v[154:157], v[184:187], v[120:123]
	v_mfma_f32_16x16x32_bf16 v[116:119], v[146:149], v[192:195], v[116:119]
	v_mfma_f32_16x16x32_bf16 v[112:115], v[154:157], v[192:195], v[112:115]
	v_mfma_f32_16x16x32_bf16 v[100:103], v[146:149], v[222:225], v[100:103]
	v_mfma_f32_16x16x32_bf16 v[96:99], v[154:157], v[222:225], v[96:99]
	v_mfma_f32_16x16x32_bf16 v[84:87], v[146:149], v[230:233], v[84:87]
	v_mfma_f32_16x16x32_bf16 v[80:83], v[154:157], v[230:233], v[80:83]
	v_mfma_f32_16x16x32_bf16 v[108:111], v[164:167], v[180:183], v[108:111]
	v_mfma_f32_16x16x32_bf16 v[104:107], v[172:175], v[180:183], v[104:107]
	v_mfma_f32_16x16x32_bf16 v[92:95], v[164:167], v[188:191], v[92:95]
	v_mfma_f32_16x16x32_bf16 v[88:91], v[172:175], v[188:191], v[88:91]
	v_mfma_f32_16x16x32_bf16 v[76:79], v[164:167], v[196:199], v[76:79]
	v_mfma_f32_16x16x32_bf16 v[72:75], v[172:175], v[196:199], v[72:75]
	v_mfma_f32_16x16x32_bf16 v[68:71], v[164:167], v[226:229], v[68:71]
	v_mfma_f32_16x16x32_bf16 v[64:67], v[172:175], v[226:229], v[64:67]
	v_mfma_f32_16x16x32_bf16 v[108:111], v[168:171], v[184:187], v[108:111]
	v_mfma_f32_16x16x32_bf16 v[104:107], v[176:179], v[184:187], v[104:107]
	v_mfma_f32_16x16x32_bf16 v[92:95], v[168:171], v[192:195], v[92:95]
	v_mfma_f32_16x16x32_bf16 v[88:91], v[176:179], v[192:195], v[88:91]
	v_mfma_f32_16x16x32_bf16 v[76:79], v[168:171], v[222:225], v[76:79]
	v_mfma_f32_16x16x32_bf16 v[72:75], v[176:179], v[222:225], v[72:75]
	v_mfma_f32_16x16x32_bf16 v[68:71], v[168:171], v[230:233], v[68:71]
	v_mfma_f32_16x16x32_bf16 v[64:67], v[176:179], v[230:233], v[64:67]
	s_barrier
	s_setprio 1
	s_add_i32 s72, s84, s24
	s_mov_b32 m0, s72
	ds_read_b128 v[180:183], v141 offset:16384
	ds_read_b128 v[184:187], v141 offset:17408
	ds_read_b128 v[188:191], v141 offset:18432
	ds_read_b128 v[192:195], v141 offset:19456
	ds_read_b128 v[196:199], v141 offset:20480
	ds_read_b128 v[222:225], v141 offset:21504
	ds_read_b128 v[226:229], v141 offset:22528
	ds_read_b128 v[230:233], v141 offset:23552
	global_load_lds_dwordx4 v160, s[52:53]
	s_add_i32 m0, s72, 0x2000
	s_add_u32 s72, s52, 0x160000
	s_addc_u32 s73, s53, 0
	s_add_i32 s84, s85, s24
	global_load_lds_dwordx4 v128, s[52:53]
	s_mov_b32 m0, s84
	s_nop 0
	global_load_lds_dwordx4 v160, s[72:73]
	s_add_i32 m0, s84, 0x2000
	s_nop 0
	global_load_lds_dwordx4 v128, s[72:73]
	s_mov_b32 m0, s28
	s_nop 0
	global_load_lds_dwordx4 v132, s[56:57]
	s_mov_b32 m0, s29
	s_nop 0
	global_load_lds_dwordx4 v130, s[56:57]
	s_add_u32 s98, s56, 0x80
	s_addc_u32 s99, s57, 0
	s_waitcnt vmcnt(8)
	s_waitcnt lgkmcnt(0)
	s_setprio 0
	s_barrier
	s_waitcnt lgkmcnt(0)
	v_mfma_f32_16x16x32_bf16 v[60:63], v[142:145], v[180:183], v[60:63]
	v_mfma_f32_16x16x32_bf16 v[56:59], v[150:153], v[180:183], v[56:59]
	v_mfma_f32_16x16x32_bf16 v[52:55], v[142:145], v[188:191], v[52:55]
	v_mfma_f32_16x16x32_bf16 v[48:51], v[150:153], v[188:191], v[48:51]
	v_mfma_f32_16x16x32_bf16 v[36:39], v[142:145], v[196:199], v[36:39]
	v_mfma_f32_16x16x32_bf16 v[32:35], v[150:153], v[196:199], v[32:35]
	v_mfma_f32_16x16x32_bf16 v[20:23], v[142:145], v[226:229], v[20:23]
	v_mfma_f32_16x16x32_bf16 v[16:19], v[150:153], v[226:229], v[16:19]
	v_mfma_f32_16x16x32_bf16 v[60:63], v[146:149], v[184:187], v[60:63]
	v_mfma_f32_16x16x32_bf16 v[56:59], v[154:157], v[184:187], v[56:59]
	v_mfma_f32_16x16x32_bf16 v[52:55], v[146:149], v[192:195], v[52:55]
	v_mfma_f32_16x16x32_bf16 v[48:51], v[154:157], v[192:195], v[48:51]
	v_mfma_f32_16x16x32_bf16 v[36:39], v[146:149], v[222:225], v[36:39]
	v_mfma_f32_16x16x32_bf16 v[32:35], v[154:157], v[222:225], v[32:35]
	v_mfma_f32_16x16x32_bf16 v[20:23], v[146:149], v[230:233], v[20:23]
	v_mfma_f32_16x16x32_bf16 v[16:19], v[154:157], v[230:233], v[16:19]
	v_mfma_f32_16x16x32_bf16 v[44:47], v[164:167], v[180:183], v[44:47]
	v_mfma_f32_16x16x32_bf16 v[40:43], v[172:175], v[180:183], v[40:43]
	v_mfma_f32_16x16x32_bf16 v[28:31], v[164:167], v[188:191], v[28:31]
	v_mfma_f32_16x16x32_bf16 v[24:27], v[172:175], v[188:191], v[24:27]
	v_mfma_f32_16x16x32_bf16 v[12:15], v[164:167], v[196:199], v[12:15]
	v_mfma_f32_16x16x32_bf16 v[8:11], v[172:175], v[196:199], v[8:11]
	v_mfma_f32_16x16x32_bf16 v[4:7], v[164:167], v[226:229], v[4:7]
	v_mfma_f32_16x16x32_bf16 v[0:3], v[172:175], v[226:229], v[0:3]
	v_mfma_f32_16x16x32_bf16 v[44:47], v[168:171], v[184:187], v[44:47]
	v_mfma_f32_16x16x32_bf16 v[40:43], v[176:179], v[184:187], v[40:43]
	v_mfma_f32_16x16x32_bf16 v[28:31], v[168:171], v[192:195], v[28:31]
	v_mfma_f32_16x16x32_bf16 v[24:27], v[176:179], v[192:195], v[24:27]
	v_mfma_f32_16x16x32_bf16 v[12:15], v[168:171], v[222:225], v[12:15]
	v_mfma_f32_16x16x32_bf16 v[8:11], v[176:179], v[222:225], v[8:11]
	v_mfma_f32_16x16x32_bf16 v[4:7], v[168:171], v[230:233], v[4:7]
	v_mfma_f32_16x16x32_bf16 v[0:3], v[176:179], v[230:233], v[0:3]
	s_barrier
; #define PG8_STAGE(bufoff, gbase, voff) do { _Pragma("unroll") for (int _i = 0; _i < 2; ++_i) \
;         __builtin_amdgcn_global_load_lds((const unsigned*)((const char*)(gbase) + (voff)[_i]), (PG8_LAS unsigned*)(lds + (bufoff) + ldsw + _i * 8192), 16, 0, 0); } while (0)
; #define PG8_LDA(dst, b, h) do { _Pragma("unroll") for (int m = 0; m < 4; ++m) _Pragma("unroll") for (int k = 0; k < 2; ++k) dst[m][k] = *(const PG8_LAS bf16x8*)(lds + PG8_SA(b, h) + aoff + m * 2048 + k * 1024); } while (0)
; #define PG8_LDB(dst, b, h) do { _Pragma("unroll") for (int n = 0; n < 2; ++n) _Pragma("unroll") for (int k = 0; k < 2; ++k) dst[n][k] = *(const PG8_LAS bf16x8*)(lds + PG8_SB(b, h) + boff + n * 2048 + k * 1024); } while (0)
; #define PG8_MMA(ai, bj, At, Bt) do { __builtin_amdgcn_s_setprio(1); _Pragma("unroll") for (int m = 0; m < 4; ++m) _Pragma("unroll") for (int n = 0; n < 2; ++n) _Pragma("unroll") for (int k = 0; k < 2; ++k) \
;         acc[ai][bj][m][n] = __builtin_amdgcn_mfma_f32_16x16x32_bf16(Bt[n][k], At[m][k], acc[ai][bj][m][n], 0, 0, 0); __builtin_amdgcn_s_setprio(0); } while (0)
; #define PG8_WAIT_V(n) asm volatile("s_waitcnt vmcnt(" #n ")" ::: "memory")
; #define PG8_WAIT_L(n) asm volatile("s_waitcnt lgkmcnt(" #n ")" ::: "memory")
; #define PG8_BAR __builtin_amdgcn_s_barrier()
; #define PG8_SCHED __builtin_amdgcn_sched_barrier(0)
; template <class Epi, class Sched, bool ALIGN_EPI = false, bool SP2 = false>
; __device__ __forceinline__ void gemm_phase(PG8_LAS unsigned char* lds, const Gemm g, const Sched& S, const Epi& E) {
;     ...
;             PG8_LDB(B0, 1, 0); PG8_LDB(B1, 1, 1); PG8_SCHED; PG8_LDA(At, 1, 0); PG8_STAGE(PG8_SA(0, 1), a2 + hstep, voffA);
;             PG8_WAIT_V(8); PG8_WAIT_L(0); PG8_BAR; PG8_MMA(0, 0, At, B0); PG8_MMA(0, 1, At, B1); PG8_BAR; PG8_SCHED;
;             PG8_LDA(At, 1, 1); PG8_STAGE(PG8_SB(1, 0), b3, voffB); PG8_STAGE(PG8_SB(1, 1), b3 + hstep, voffB); PG8_STAGE(PG8_SA(1, 0), a3, voffA);
;             PG8_WAIT_V(8); PG8_WAIT_L(0); PG8_BAR; PG8_MMA(1, 0, At, B0); PG8_MMA(1, 1, At, B1); PG8_BAR; PG8_SCHED;
	s_setprio 1
	s_add_i32 s72, 0, 0x18000
	s_add_i32 s73, 0, 0x1c000
	ds_read_b128 v[142:145], v200 offset:32768
	ds_read_b128 v[146:149], v200 offset:33792
	ds_read_b128 v[150:153], v200 offset:34816
	ds_read_b128 v[154:157], v200 offset:35840
	ds_read_b128 v[164:167], v200 offset:49152
	ds_read_b128 v[168:171], v200 offset:50176
	ds_read_b128 v[172:175], v200 offset:51200
	ds_read_b128 v[176:179], v200 offset:52224
	s_add_u32 s56, s56, 0x160000
	s_addc_u32 s57, s57, 0
	s_mov_b32 m0, s59
	ds_read_b128 v[180:183], v141 offset:32768
	ds_read_b128 v[184:187], v141 offset:33792
	ds_read_b128 v[188:191], v141 offset:34816
	ds_read_b128 v[192:195], v141 offset:35840
	ds_read_b128 v[196:199], v141 offset:36864
	ds_read_b128 v[222:225], v141 offset:37888
	ds_read_b128 v[226:229], v141 offset:38912
	ds_read_b128 v[230:233], v141 offset:39936
	global_load_lds_dwordx4 v132, s[56:57]
	s_mov_b32 m0, s63
	s_nop 0
	global_load_lds_dwordx4 v130, s[56:57]
	s_waitcnt vmcnt(8)
	s_waitcnt lgkmcnt(0)
	s_setprio 0
	s_barrier
	s_waitcnt lgkmcnt(0)
	v_mfma_f32_16x16x32_bf16 v[124:127], v[142:145], v[180:183], v[124:127]
	v_mfma_f32_16x16x32_bf16 v[120:123], v[150:153], v[180:183], v[120:123]
	v_mfma_f32_16x16x32_bf16 v[116:119], v[142:145], v[188:191], v[116:119]
	v_mfma_f32_16x16x32_bf16 v[112:115], v[150:153], v[188:191], v[112:115]
	v_mfma_f32_16x16x32_bf16 v[100:103], v[142:145], v[196:199], v[100:103]
	v_mfma_f32_16x16x32_bf16 v[96:99], v[150:153], v[196:199], v[96:99]
	v_mfma_f32_16x16x32_bf16 v[84:87], v[142:145], v[226:229], v[84:87]
	v_mfma_f32_16x16x32_bf16 v[80:83], v[150:153], v[226:229], v[80:83]
	v_mfma_f32_16x16x32_bf16 v[124:127], v[146:149], v[184:187], v[124:127]
	v_mfma_f32_16x16x32_bf16 v[120:123], v[154:157], v[184:187], v[120:123]
	v_mfma_f32_16x16x32_bf16 v[116:119], v[146:149], v[192:195], v[116:119]
	v_mfma_f32_16x16x32_bf16 v[112:115], v[154:157], v[192:195], v[112:115]
	v_mfma_f32_16x16x32_bf16 v[100:103], v[146:149], v[222:225], v[100:103]
	v_mfma_f32_16x16x32_bf16 v[96:99], v[154:157], v[222:225], v[96:99]
	v_mfma_f32_16x16x32_bf16 v[84:87], v[146:149], v[230:233], v[84:87]
	v_mfma_f32_16x16x32_bf16 v[80:83], v[154:157], v[230:233], v[80:83]
	v_mfma_f32_16x16x32_bf16 v[108:111], v[164:167], v[180:183], v[108:111]
	v_mfma_f32_16x16x32_bf16 v[104:107], v[172:175], v[180:183], v[104:107]
	v_mfma_f32_16x16x32_bf16 v[92:95], v[164:167], v[188:191], v[92:95]
	v_mfma_f32_16x16x32_bf16 v[88:91], v[172:175], v[188:191], v[88:91]
	v_mfma_f32_16x16x32_bf16 v[76:79], v[164:167], v[196:199], v[76:79]
	v_mfma_f32_16x16x32_bf16 v[72:75], v[172:175], v[196:199], v[72:75]
	v_mfma_f32_16x16x32_bf16 v[68:71], v[164:167], v[226:229], v[68:71]
	v_mfma_f32_16x16x32_bf16 v[64:67], v[172:175], v[226:229], v[64:67]
	v_mfma_f32_16x16x32_bf16 v[108:111], v[168:171], v[184:187], v[108:111]
	v_mfma_f32_16x16x32_bf16 v[104:107], v[176:179], v[184:187], v[104:107]
	v_mfma_f32_16x16x32_bf16 v[92:95], v[168:171], v[192:195], v[92:95]
	v_mfma_f32_16x16x32_bf16 v[88:91], v[176:179], v[192:195], v[88:91]
	v_mfma_f32_16x16x32_bf16 v[76:79], v[168:171], v[222:225], v[76:79]
	v_mfma_f32_16x16x32_bf16 v[72:75], v[176:179], v[222:225], v[72:75]
	v_mfma_f32_16x16x32_bf16 v[68:71], v[168:171], v[230:233], v[68:71]
	v_mfma_f32_16x16x32_bf16 v[64:67], v[176:179], v[230:233], v[64:67]
	s_barrier
	s_setprio 1
	s_add_i32 s56, s72, s24
	s_mov_b32 m0, s56
	ds_read_b128 v[180:183], v141 offset:49152
	ds_read_b128 v[184:187], v141 offset:50176
	ds_read_b128 v[188:191], v141 offset:51200
	ds_read_b128 v[192:195], v141 offset:52224
	ds_read_b128 v[196:199], v141 offset:53248
	ds_read_b128 v[222:225], v141 offset:54272
	ds_read_b128 v[226:229], v141 offset:55296
	ds_read_b128 v[230:233], v141 offset:56320
	s_add_u32 s52, s52, 0x80
	s_addc_u32 s53, s53, 0
	global_load_lds_dwordx4 v160, s[52:53]
	s_add_i32 m0, s56, 0x2000
	s_add_i32 s56, s73, s24
	global_load_lds_dwordx4 v128, s[52:53]
	s_add_u32 s52, s52, 0x160000
	s_addc_u32 s53, s53, 0
	s_mov_b32 m0, s56
	s_nop 0
	global_load_lds_dwordx4 v160, s[52:53]
	s_add_i32 m0, s56, 0x2000
	s_nop 0
	global_load_lds_dwordx4 v128, s[52:53]
	s_mov_b32 m0, s74
	s_nop 0
	global_load_lds_dwordx4 v132, s[98:99]
	s_mov_b32 m0, s75
	s_nop 0
	global_load_lds_dwordx4 v130, s[98:99]
	s_waitcnt vmcnt(8)
	s_waitcnt lgkmcnt(0)
	s_setprio 0
	s_barrier
	s_waitcnt lgkmcnt(0)
	v_mfma_f32_16x16x32_bf16 v[60:63], v[142:145], v[180:183], v[60:63]
	v_mfma_f32_16x16x32_bf16 v[56:59], v[150:153], v[180:183], v[56:59]
	v_mfma_f32_16x16x32_bf16 v[52:55], v[142:145], v[188:191], v[52:55]
	v_mfma_f32_16x16x32_bf16 v[48:51], v[150:153], v[188:191], v[48:51]
	v_mfma_f32_16x16x32_bf16 v[36:39], v[142:145], v[196:199], v[36:39]
	v_mfma_f32_16x16x32_bf16 v[32:35], v[150:153], v[196:199], v[32:35]
	v_mfma_f32_16x16x32_bf16 v[20:23], v[142:145], v[226:229], v[20:23]
	v_mfma_f32_16x16x32_bf16 v[16:19], v[150:153], v[226:229], v[16:19]
	v_mfma_f32_16x16x32_bf16 v[60:63], v[146:149], v[184:187], v[60:63]
	v_mfma_f32_16x16x32_bf16 v[56:59], v[154:157], v[184:187], v[56:59]
	v_mfma_f32_16x16x32_bf16 v[52:55], v[146:149], v[192:195], v[52:55]
	v_mfma_f32_16x16x32_bf16 v[48:51], v[154:157], v[192:195], v[48:51]
	v_mfma_f32_16x16x32_bf16 v[36:39], v[146:149], v[222:225], v[36:39]
	v_mfma_f32_16x16x32_bf16 v[32:35], v[154:157], v[222:225], v[32:35]
	v_mfma_f32_16x16x32_bf16 v[20:23], v[146:149], v[230:233], v[20:23]
	v_mfma_f32_16x16x32_bf16 v[16:19], v[154:157], v[230:233], v[16:19]
	v_mfma_f32_16x16x32_bf16 v[44:47], v[164:167], v[180:183], v[44:47]
	v_mfma_f32_16x16x32_bf16 v[40:43], v[172:175], v[180:183], v[40:43]
	v_mfma_f32_16x16x32_bf16 v[28:31], v[164:167], v[188:191], v[28:31]
	v_mfma_f32_16x16x32_bf16 v[24:27], v[172:175], v[188:191], v[24:27]
	v_mfma_f32_16x16x32_bf16 v[12:15], v[164:167], v[196:199], v[12:15]
	v_mfma_f32_16x16x32_bf16 v[8:11], v[172:175], v[196:199], v[8:11]
	v_mfma_f32_16x16x32_bf16 v[4:7], v[164:167], v[226:229], v[4:7]
	v_mfma_f32_16x16x32_bf16 v[0:3], v[172:175], v[226:229], v[0:3]
	v_mfma_f32_16x16x32_bf16 v[44:47], v[168:171], v[184:187], v[44:47]
	v_mfma_f32_16x16x32_bf16 v[40:43], v[176:179], v[184:187], v[40:43]
	v_mfma_f32_16x16x32_bf16 v[28:31], v[168:171], v[192:195], v[28:31]
	v_mfma_f32_16x16x32_bf16 v[24:27], v[176:179], v[192:195], v[24:27]
	v_mfma_f32_16x16x32_bf16 v[12:15], v[168:171], v[222:225], v[12:15]
	v_mfma_f32_16x16x32_bf16 v[8:11], v[176:179], v[222:225], v[8:11]
	v_mfma_f32_16x16x32_bf16 v[4:7], v[168:171], v[230:233], v[4:7]
	v_mfma_f32_16x16x32_bf16 v[0:3], v[176:179], v[230:233], v[0:3]
	s_barrier
	s_add_i32 s83, s83, 2
	s_add_u32 s81, s81, 0x100
	s_addc_u32 s82, s82, 0
	s_cmpk_gt_u32 s83, 0x55
	s_mov_b64 s[72:73], s[4:5]
	s_cbranch_scc0 .LBB0_52
	s_and_b64 vcc, exec, s[42:43]
	s_cbranch_vccz .LBB0_55
	s_barrier

; #define PG8_STAGE(bufoff, gbase, voff) do { _Pragma("unroll") for (int _i = 0; _i < 2; ++_i) \
;         __builtin_amdgcn_global_load_lds((const unsigned*)((const char*)(gbase) + (voff)[_i]), (PG8_LAS unsigned*)(lds + (bufoff) + ldsw + _i * 8192), 16, 0, 0); } while (0)
; #define PG8_LDA(dst, b, h) do { _Pragma("unroll") for (int m = 0; m < 4; ++m) _Pragma("unroll") for (int k = 0; k < 2; ++k) dst[m][k] = *(const PG8_LAS bf16x8*)(lds + PG8_SA(b, h) + aoff + m * 2048 + k * 1024); } while (0)
; #define PG8_LDB(dst, b, h) do { _Pragma("unroll") for (int n = 0; n < 2; ++n) _Pragma("unroll") for (int k = 0; k < 2; ++k) dst[n][k] = *(const PG8_LAS bf16x8*)(lds + PG8_SB(b, h) + boff + n * 2048 + k * 1024); } while (0)
; #define PG8_MMA(ai, bj, At, Bt) do { __builtin_amdgcn_s_setprio(1); _Pragma("unroll") for (int m = 0; m < 4; ++m) _Pragma("unroll") for (int n = 0; n < 2; ++n) _Pragma("unroll") for (int k = 0; k < 2; ++k) \
;         acc[ai][bj][m][n] = __builtin_amdgcn_mfma_f32_16x16x32_bf16(Bt[n][k], At[m][k], acc[ai][bj][m][n], 0, 0, 0); __builtin_amdgcn_s_setprio(0); } while (0)
; #define PG8_WAIT_V(n) asm volatile("s_waitcnt vmcnt(" #n ")" ::: "memory")
; #define PG8_WAIT_L(n) asm volatile("s_waitcnt lgkmcnt(" #n ")" ::: "memory")
; #define PG8_BAR __builtin_amdgcn_s_barrier()
; template <class Epi, class Sched, bool ALIGN_EPI = false, bool SP2 = false>
; __device__ __forceinline__ void gemm_phase(PG8_LAS unsigned char* lds, const Gemm g, const Sched& S, const Epi& E) {
;     ...
;             const char* a1 = cA + (size_t)(t + 1) * kstep;
;             const char* a2 = last ? nA : cA + (size_t)(t + 2) * kstep; const char* b2 = last ? nB : cB + (size_t)(t + 2) * kstep;
;             const char* a3 = a2 + kstep; const char* b3 = b2 + kstep;
;             if (last && has_next) S.a_ready(nxt);
;             if constexpr (SP2) {
;             PG8_LDB(B0, 0, 0); PG8_LDB(B1, 0, 1); PG8_SCHED; PG8_LDA(At, 0, 0); PG8_STAGE(PG8_SA(1, 1), a1 + hstep, voffA);
;             PG8_WAIT_V(8); PG8_WAIT_L(0); PG8_BAR; PG8_MMA(0, 0, At, B0); PG8_MMA(0, 1, At, B1); PG8_BAR; PG8_SCHED;
;             PG8_LDA(At, 0, 1); PG8_STAGE(PG8_SB(0, 0), b2, voffB); PG8_STAGE(PG8_SB(0, 1), b2 + hstep, voffB); PG8_STAGE(PG8_SA(0, 0), a2, voffA);
;             PG8_WAIT_V(8); PG8_WAIT_L(0); PG8_BAR; PG8_MMA(1, 0, At, B0); PG8_MMA(1, 1, At, B1); PG8_BAR; PG8_SCHED;
.LBB0_86:
	s_setprio 1
	s_add_i32 s88, 0, 0x10000
	s_add_i32 s90, 0, 0x14000
	ds_read_b128 v[140:143], v200
	ds_read_b128 v[150:153], v200 offset:1024
	ds_read_b128 v[154:157], v200 offset:2048
	ds_read_b128 v[164:167], v200 offset:3072
	ds_read_b128 v[168:171], v200 offset:16384
	ds_read_b128 v[172:175], v200 offset:17408
	ds_read_b128 v[176:179], v200 offset:18432
	ds_read_b128 v[180:183], v200 offset:19456
	s_add_i32 m0, s63, 0xc000
	ds_read_b128 v[184:187], v149
	ds_read_b128 v[188:191], v149 offset:1024
	ds_read_b128 v[192:195], v149 offset:2048
	ds_read_b128 v[196:199], v149 offset:3072
	ds_read_b128 v[222:225], v149 offset:4096
	ds_read_b128 v[226:229], v149 offset:5120
	ds_read_b128 v[230:233], v149 offset:6144
	ds_read_b128 v[234:237], v149 offset:7168
	global_load_lds_dwordx4 v136, s[82:83]
	s_add_i32 m0, s63, 0xe000
	s_nop 0
	global_load_lds_dwordx4 v138, s[82:83]
	s_add_u32 s4, s82, 0xfffc0080
	s_addc_u32 s5, s83, -1
	s_cmp_eq_u32 s87, 12
	s_cselect_b32 s53, s7, s5
	s_cselect_b32 s52, s15, s4
	s_cselect_b32 s5, s24, s43
	s_cselect_b32 s4, s28, s29
	s_waitcnt vmcnt(8)
	s_waitcnt lgkmcnt(0)
	s_setprio 0
	s_barrier
	s_waitcnt lgkmcnt(0)
	v_mfma_f32_16x16x32_bf16 v[124:127], v[140:143], v[184:187], v[124:127]
	v_mfma_f32_16x16x32_bf16 v[120:123], v[154:157], v[184:187], v[120:123]
	v_mfma_f32_16x16x32_bf16 v[108:111], v[140:143], v[192:195], v[108:111]
	v_mfma_f32_16x16x32_bf16 v[104:107], v[154:157], v[192:195], v[104:107]
	v_mfma_f32_16x16x32_bf16 v[92:95], v[140:143], v[222:225], v[92:95]
	v_mfma_f32_16x16x32_bf16 v[88:91], v[154:157], v[222:225], v[88:91]
	v_mfma_f32_16x16x32_bf16 v[76:79], v[140:143], v[230:233], v[76:79]
	v_mfma_f32_16x16x32_bf16 v[72:75], v[154:157], v[230:233], v[72:75]
	v_mfma_f32_16x16x32_bf16 v[124:127], v[150:153], v[188:191], v[124:127]
	v_mfma_f32_16x16x32_bf16 v[120:123], v[164:167], v[188:191], v[120:123]
	v_mfma_f32_16x16x32_bf16 v[108:111], v[150:153], v[196:199], v[108:111]
	v_mfma_f32_16x16x32_bf16 v[104:107], v[164:167], v[196:199], v[104:107]
	v_mfma_f32_16x16x32_bf16 v[92:95], v[150:153], v[226:229], v[92:95]
	v_mfma_f32_16x16x32_bf16 v[88:91], v[164:167], v[226:229], v[88:91]
	v_mfma_f32_16x16x32_bf16 v[76:79], v[150:153], v[234:237], v[76:79]
	v_mfma_f32_16x16x32_bf16 v[72:75], v[164:167], v[234:237], v[72:75]
	v_mfma_f32_16x16x32_bf16 v[116:119], v[168:171], v[184:187], v[116:119]
	v_mfma_f32_16x16x32_bf16 v[112:115], v[176:179], v[184:187], v[112:115]
	v_mfma_f32_16x16x32_bf16 v[100:103], v[168:171], v[192:195], v[100:103]
	v_mfma_f32_16x16x32_bf16 v[96:99], v[176:179], v[192:195], v[96:99]
	v_mfma_f32_16x16x32_bf16 v[84:87], v[168:171], v[222:225], v[84:87]
	v_mfma_f32_16x16x32_bf16 v[80:83], v[176:179], v[222:225], v[80:83]
	v_mfma_f32_16x16x32_bf16 v[68:71], v[168:171], v[230:233], v[68:71]
	v_mfma_f32_16x16x32_bf16 v[64:67], v[176:179], v[230:233], v[64:67]
	v_mfma_f32_16x16x32_bf16 v[116:119], v[172:175], v[188:191], v[116:119]
	v_mfma_f32_16x16x32_bf16 v[112:115], v[180:183], v[188:191], v[112:115]
	v_mfma_f32_16x16x32_bf16 v[100:103], v[172:175], v[196:199], v[100:103]
	v_mfma_f32_16x16x32_bf16 v[96:99], v[180:183], v[196:199], v[96:99]
	v_mfma_f32_16x16x32_bf16 v[84:87], v[172:175], v[226:229], v[84:87]
	v_mfma_f32_16x16x32_bf16 v[80:83], v[180:183], v[226:229], v[80:83]
	v_mfma_f32_16x16x32_bf16 v[68:71], v[172:175], v[234:237], v[68:71]
	v_mfma_f32_16x16x32_bf16 v[64:67], v[180:183], v[234:237], v[64:67]
	s_barrier
	s_setprio 1
	s_add_i32 s88, s88, s59
	s_mov_b32 m0, s88
	ds_read_b128 v[184:187], v149 offset:16384
	ds_read_b128 v[188:191], v149 offset:17408
	ds_read_b128 v[192:195], v149 offset:18432
	ds_read_b128 v[196:199], v149 offset:19456
	ds_read_b128 v[222:225], v149 offset:20480
	ds_read_b128 v[226:229], v149 offset:21504
	ds_read_b128 v[230:233], v149 offset:22528
	ds_read_b128 v[234:237], v149 offset:23552
	global_load_lds_dwordx4 v130, s[4:5]
	s_add_i32 m0, s88, 0x2000
	s_add_u32 s88, s4, 0x40000
	s_addc_u32 s89, s5, 0
	s_add_i32 s90, s90, s59
	global_load_lds_dwordx4 v134, s[4:5]
	s_mov_b32 m0, s90
	s_nop 0
	global_load_lds_dwordx4 v130, s[88:89]
	s_add_i32 m0, s90, 0x2000
	s_nop 0
	global_load_lds_dwordx4 v134, s[88:89]
	s_mov_b32 m0, s63
	s_nop 0
	global_load_lds_dwordx4 v128, s[52:53]
	s_mov_b32 m0, s74
	s_nop 0
	global_load_lds_dwordx4 v132, s[52:53]
	s_add_u32 s98, s52, 0x80
	s_addc_u32 s99, s53, 0
	s_waitcnt vmcnt(8)
	s_waitcnt lgkmcnt(0)
	s_setprio 0
	s_barrier
	s_waitcnt lgkmcnt(0)
	v_mfma_f32_16x16x32_bf16 v[60:63], v[140:143], v[184:187], v[60:63]
	v_mfma_f32_16x16x32_bf16 v[56:59], v[154:157], v[184:187], v[56:59]
	v_mfma_f32_16x16x32_bf16 v[44:47], v[140:143], v[192:195], v[44:47]
	v_mfma_f32_16x16x32_bf16 v[40:43], v[154:157], v[192:195], v[40:43]
	v_mfma_f32_16x16x32_bf16 v[28:31], v[140:143], v[222:225], v[28:31]
	v_mfma_f32_16x16x32_bf16 v[24:27], v[154:157], v[222:225], v[24:27]
	v_mfma_f32_16x16x32_bf16 v[12:15], v[140:143], v[230:233], v[12:15]
	v_mfma_f32_16x16x32_bf16 v[8:11], v[154:157], v[230:233], v[8:11]
	v_mfma_f32_16x16x32_bf16 v[60:63], v[150:153], v[188:191], v[60:63]
	v_mfma_f32_16x16x32_bf16 v[56:59], v[164:167], v[188:191], v[56:59]
	v_mfma_f32_16x16x32_bf16 v[44:47], v[150:153], v[196:199], v[44:47]
	v_mfma_f32_16x16x32_bf16 v[40:43], v[164:167], v[196:199], v[40:43]
	v_mfma_f32_16x16x32_bf16 v[28:31], v[150:153], v[226:229], v[28:31]
	v_mfma_f32_16x16x32_bf16 v[24:27], v[164:167], v[226:229], v[24:27]
	v_mfma_f32_16x16x32_bf16 v[12:15], v[150:153], v[234:237], v[12:15]
	v_mfma_f32_16x16x32_bf16 v[8:11], v[164:167], v[234:237], v[8:11]
	v_mfma_f32_16x16x32_bf16 v[52:55], v[168:171], v[184:187], v[52:55]
	v_mfma_f32_16x16x32_bf16 v[48:51], v[176:179], v[184:187], v[48:51]
	v_mfma_f32_16x16x32_bf16 v[36:39], v[168:171], v[192:195], v[36:39]
	v_mfma_f32_16x16x32_bf16 v[32:35], v[176:179], v[192:195], v[32:35]
	v_mfma_f32_16x16x32_bf16 v[20:23], v[168:171], v[222:225], v[20:23]
	v_mfma_f32_16x16x32_bf16 v[16:19], v[176:179], v[222:225], v[16:19]
	v_mfma_f32_16x16x32_bf16 v[4:7], v[168:171], v[230:233], v[4:7]
	v_mfma_f32_16x16x32_bf16 v[0:3], v[176:179], v[230:233], v[0:3]
	v_mfma_f32_16x16x32_bf16 v[52:55], v[172:175], v[188:191], v[52:55]
	v_mfma_f32_16x16x32_bf16 v[48:51], v[180:183], v[188:191], v[48:51]
	v_mfma_f32_16x16x32_bf16 v[36:39], v[172:175], v[196:199], v[36:39]
	v_mfma_f32_16x16x32_bf16 v[32:35], v[180:183], v[196:199], v[32:35]
	v_mfma_f32_16x16x32_bf16 v[20:23], v[172:175], v[226:229], v[20:23]
	v_mfma_f32_16x16x32_bf16 v[16:19], v[180:183], v[226:229], v[16:19]
	v_mfma_f32_16x16x32_bf16 v[4:7], v[172:175], v[234:237], v[4:7]
	v_mfma_f32_16x16x32_bf16 v[0:3], v[180:183], v[234:237], v[0:3]
	s_barrier
; #define PG8_STAGE(bufoff, gbase, voff) do { _Pragma("unroll") for (int _i = 0; _i < 2; ++_i) \
;         __builtin_amdgcn_global_load_lds((const unsigned*)((const char*)(gbase) + (voff)[_i]), (PG8_LAS unsigned*)(lds + (bufoff) + ldsw + _i * 8192), 16, 0, 0); } while (0)
; #define PG8_LDA(dst, b, h) do { _Pragma("unroll") for (int m = 0; m < 4; ++m) _Pragma("unroll") for (int k = 0; k < 2; ++k) dst[m][k] = *(const PG8_LAS bf16x8*)(lds + PG8_SA(b, h) + aoff + m * 2048 + k * 1024); } while (0)
; #define PG8_LDB(dst, b, h) do { _Pragma("unroll") for (int n = 0; n < 2; ++n) _Pragma("unroll") for (int k = 0; k < 2; ++k) dst[n][k] = *(const PG8_LAS bf16x8*)(lds + PG8_SB(b, h) + boff + n * 2048 + k * 1024); } while (0)
; #define PG8_MMA(ai, bj, At, Bt) do { __builtin_amdgcn_s_setprio(1); _Pragma("unroll") for (int m = 0; m < 4; ++m) _Pragma("unroll") for (int n = 0; n < 2; ++n) _Pragma("unroll") for (int k = 0; k < 2; ++k) \
;         acc[ai][bj][m][n] = __builtin_amdgcn_mfma_f32_16x16x32_bf16(Bt[n][k], At[m][k], acc[ai][bj][m][n], 0, 0, 0); __builtin_amdgcn_s_setprio(0); } while (0)
; #define PG8_WAIT_V(n) asm volatile("s_waitcnt vmcnt(" #n ")" ::: "memory")
; #define PG8_WAIT_L(n) asm volatile("s_waitcnt lgkmcnt(" #n ")" ::: "memory")
; #define PG8_BAR __builtin_amdgcn_s_barrier()
; #define PG8_SCHED __builtin_amdgcn_sched_barrier(0)
; template <class Epi, class Sched, bool ALIGN_EPI = false, bool SP2 = false>
; __device__ __forceinline__ void gemm_phase(PG8_LAS unsigned char* lds, const Gemm g, const Sched& S, const Epi& E) {
;     ...
;             PG8_LDB(B0, 1, 0); PG8_LDB(B1, 1, 1); PG8_SCHED; PG8_LDA(At, 1, 0); PG8_STAGE(PG8_SA(0, 1), a2 + hstep, voffA);
;             PG8_WAIT_V(8); PG8_WAIT_L(0); PG8_BAR; PG8_MMA(0, 0, At, B0); PG8_MMA(0, 1, At, B1); PG8_BAR; PG8_SCHED;
;             PG8_LDA(At, 1, 1); PG8_STAGE(PG8_SB(1, 0), b3, voffB); PG8_STAGE(PG8_SB(1, 1), b3 + hstep, voffB); PG8_STAGE(PG8_SA(1, 0), a3, voffA);
;             PG8_WAIT_V(8); PG8_WAIT_L(0); PG8_BAR; PG8_MMA(1, 0, At, B0); PG8_MMA(1, 1, At, B1); PG8_BAR; PG8_SCHED;
	s_setprio 1
	s_add_i32 s88, 0, 0x18000
	s_add_i32 s89, 0, 0x1c000
	ds_read_b128 v[140:143], v200 offset:32768
	ds_read_b128 v[150:153], v200 offset:33792
	ds_read_b128 v[154:157], v200 offset:34816
	ds_read_b128 v[164:167], v200 offset:35840
	ds_read_b128 v[168:171], v200 offset:49152
	ds_read_b128 v[172:175], v200 offset:50176
	ds_read_b128 v[176:179], v200 offset:51200
	ds_read_b128 v[180:183], v200 offset:52224
	s_add_u32 s52, s52, 0x40000
	s_addc_u32 s53, s53, 0
	s_mov_b32 m0, s75
	ds_read_b128 v[184:187], v149 offset:32768
	ds_read_b128 v[188:191], v149 offset:33792
	ds_read_b128 v[192:195], v149 offset:34816
	ds_read_b128 v[196:199], v149 offset:35840
	ds_read_b128 v[222:225], v149 offset:36864
	ds_read_b128 v[226:229], v149 offset:37888
	ds_read_b128 v[230:233], v149 offset:38912
	ds_read_b128 v[234:237], v149 offset:39936
	global_load_lds_dwordx4 v128, s[52:53]
	s_mov_b32 m0, s81
	s_nop 0
	global_load_lds_dwordx4 v132, s[52:53]
	s_waitcnt vmcnt(8)
	s_waitcnt lgkmcnt(0)
	s_setprio 0
	s_barrier
	s_waitcnt lgkmcnt(0)
	v_mfma_f32_16x16x32_bf16 v[124:127], v[140:143], v[184:187], v[124:127]
	v_mfma_f32_16x16x32_bf16 v[120:123], v[154:157], v[184:187], v[120:123]
	v_mfma_f32_16x16x32_bf16 v[108:111], v[140:143], v[192:195], v[108:111]
	v_mfma_f32_16x16x32_bf16 v[104:107], v[154:157], v[192:195], v[104:107]
	v_mfma_f32_16x16x32_bf16 v[92:95], v[140:143], v[222:225], v[92:95]
	v_mfma_f32_16x16x32_bf16 v[88:91], v[154:157], v[222:225], v[88:91]
	v_mfma_f32_16x16x32_bf16 v[76:79], v[140:143], v[230:233], v[76:79]
	v_mfma_f32_16x16x32_bf16 v[72:75], v[154:157], v[230:233], v[72:75]
	v_mfma_f32_16x16x32_bf16 v[124:127], v[150:153], v[188:191], v[124:127]
	v_mfma_f32_16x16x32_bf16 v[120:123], v[164:167], v[188:191], v[120:123]
	v_mfma_f32_16x16x32_bf16 v[108:111], v[150:153], v[196:199], v[108:111]
	v_mfma_f32_16x16x32_bf16 v[104:107], v[164:167], v[196:199], v[104:107]
	v_mfma_f32_16x16x32_bf16 v[92:95], v[150:153], v[226:229], v[92:95]
	v_mfma_f32_16x16x32_bf16 v[88:91], v[164:167], v[226:229], v[88:91]
	v_mfma_f32_16x16x32_bf16 v[76:79], v[150:153], v[234:237], v[76:79]
	v_mfma_f32_16x16x32_bf16 v[72:75], v[164:167], v[234:237], v[72:75]
	v_mfma_f32_16x16x32_bf16 v[116:119], v[168:171], v[184:187], v[116:119]
	v_mfma_f32_16x16x32_bf16 v[112:115], v[176:179], v[184:187], v[112:115]
	v_mfma_f32_16x16x32_bf16 v[100:103], v[168:171], v[192:195], v[100:103]
	v_mfma_f32_16x16x32_bf16 v[96:99], v[176:179], v[192:195], v[96:99]
	v_mfma_f32_16x16x32_bf16 v[84:87], v[168:171], v[222:225], v[84:87]
	v_mfma_f32_16x16x32_bf16 v[80:83], v[176:179], v[222:225], v[80:83]
	v_mfma_f32_16x16x32_bf16 v[68:71], v[168:171], v[230:233], v[68:71]
	v_mfma_f32_16x16x32_bf16 v[64:67], v[176:179], v[230:233], v[64:67]
	v_mfma_f32_16x16x32_bf16 v[116:119], v[172:175], v[188:191], v[116:119]
	v_mfma_f32_16x16x32_bf16 v[112:115], v[180:183], v[188:191], v[112:115]
	v_mfma_f32_16x16x32_bf16 v[100:103], v[172:175], v[196:199], v[100:103]
	v_mfma_f32_16x16x32_bf16 v[96:99], v[180:183], v[196:199], v[96:99]
	v_mfma_f32_16x16x32_bf16 v[84:87], v[172:175], v[226:229], v[84:87]
	v_mfma_f32_16x16x32_bf16 v[80:83], v[180:183], v[226:229], v[80:83]
	v_mfma_f32_16x16x32_bf16 v[68:71], v[172:175], v[234:237], v[68:71]
	v_mfma_f32_16x16x32_bf16 v[64:67], v[180:183], v[234:237], v[64:67]
	s_barrier
	s_setprio 1
	s_add_i32 s52, s88, s59
	s_mov_b32 m0, s52
	ds_read_b128 v[184:187], v149 offset:49152
	ds_read_b128 v[188:191], v149 offset:50176
	ds_read_b128 v[192:195], v149 offset:51200
	ds_read_b128 v[196:199], v149 offset:52224
	ds_read_b128 v[222:225], v149 offset:53248
	ds_read_b128 v[226:229], v149 offset:54272
	ds_read_b128 v[230:233], v149 offset:55296
	ds_read_b128 v[234:237], v149 offset:56320
	s_add_u32 s4, s4, 0x80
	s_addc_u32 s5, s5, 0
	global_load_lds_dwordx4 v130, s[4:5]
	s_add_i32 m0, s52, 0x2000
	s_add_i32 s52, s89, s59
	global_load_lds_dwordx4 v134, s[4:5]
	s_add_u32 s4, s4, 0x40000
	s_addc_u32 s5, s5, 0
	s_mov_b32 m0, s52
	s_nop 0
	global_load_lds_dwordx4 v130, s[4:5]
	s_add_i32 m0, s52, 0x2000
	s_nop 0
	global_load_lds_dwordx4 v134, s[4:5]
	s_mov_b32 m0, s84
	s_nop 0
	global_load_lds_dwordx4 v128, s[98:99]
	s_mov_b32 m0, s85
	s_nop 0
	global_load_lds_dwordx4 v132, s[98:99]
	s_waitcnt vmcnt(8)
	s_waitcnt lgkmcnt(0)
	s_setprio 0
	s_barrier
	s_waitcnt lgkmcnt(0)
	v_mfma_f32_16x16x32_bf16 v[60:63], v[140:143], v[184:187], v[60:63]
	v_mfma_f32_16x16x32_bf16 v[56:59], v[154:157], v[184:187], v[56:59]
	v_mfma_f32_16x16x32_bf16 v[44:47], v[140:143], v[192:195], v[44:47]
	v_mfma_f32_16x16x32_bf16 v[40:43], v[154:157], v[192:195], v[40:43]
	v_mfma_f32_16x16x32_bf16 v[28:31], v[140:143], v[222:225], v[28:31]
	v_mfma_f32_16x16x32_bf16 v[24:27], v[154:157], v[222:225], v[24:27]
	v_mfma_f32_16x16x32_bf16 v[12:15], v[140:143], v[230:233], v[12:15]
	v_mfma_f32_16x16x32_bf16 v[8:11], v[154:157], v[230:233], v[8:11]
	v_mfma_f32_16x16x32_bf16 v[60:63], v[150:153], v[188:191], v[60:63]
	v_mfma_f32_16x16x32_bf16 v[56:59], v[164:167], v[188:191], v[56:59]
	v_mfma_f32_16x16x32_bf16 v[44:47], v[150:153], v[196:199], v[44:47]
	v_mfma_f32_16x16x32_bf16 v[40:43], v[164:167], v[196:199], v[40:43]
	v_mfma_f32_16x16x32_bf16 v[28:31], v[150:153], v[226:229], v[28:31]
	v_mfma_f32_16x16x32_bf16 v[24:27], v[164:167], v[226:229], v[24:27]
	v_mfma_f32_16x16x32_bf16 v[12:15], v[150:153], v[234:237], v[12:15]
	v_mfma_f32_16x16x32_bf16 v[8:11], v[164:167], v[234:237], v[8:11]
	v_mfma_f32_16x16x32_bf16 v[52:55], v[168:171], v[184:187], v[52:55]
	v_mfma_f32_16x16x32_bf16 v[48:51], v[176:179], v[184:187], v[48:51]
	v_mfma_f32_16x16x32_bf16 v[36:39], v[168:171], v[192:195], v[36:39]
	v_mfma_f32_16x16x32_bf16 v[32:35], v[176:179], v[192:195], v[32:35]
	v_mfma_f32_16x16x32_bf16 v[20:23], v[168:171], v[222:225], v[20:23]
	v_mfma_f32_16x16x32_bf16 v[16:19], v[176:179], v[222:225], v[16:19]
	v_mfma_f32_16x16x32_bf16 v[4:7], v[168:171], v[230:233], v[4:7]
	v_mfma_f32_16x16x32_bf16 v[0:3], v[176:179], v[230:233], v[0:3]
	v_mfma_f32_16x16x32_bf16 v[52:55], v[172:175], v[188:191], v[52:55]
	v_mfma_f32_16x16x32_bf16 v[48:51], v[180:183], v[188:191], v[48:51]
	v_mfma_f32_16x16x32_bf16 v[36:39], v[172:175], v[196:199], v[36:39]
	v_mfma_f32_16x16x32_bf16 v[32:35], v[180:183], v[196:199], v[32:35]
	v_mfma_f32_16x16x32_bf16 v[20:23], v[172:175], v[226:229], v[20:23]
	v_mfma_f32_16x16x32_bf16 v[16:19], v[180:183], v[226:229], v[16:19]
	v_mfma_f32_16x16x32_bf16 v[4:7], v[172:175], v[234:237], v[4:7]
	v_mfma_f32_16x16x32_bf16 v[0:3], v[180:183], v[234:237], v[0:3]
	s_barrier
	s_add_i32 s87, s87, 2
	s_add_u32 s82, s82, 0x100
	s_addc_u32 s83, s83, 0
	s_add_u32 s29, s29, 0x100
	s_addc_u32 s43, s43, 0
	s_cmp_gt_u32 s87, 13
	s_cbranch_scc0 .LBB0_86
	s_and_b64 vcc, exec, s[12:13]
	s_cbranch_vccz .LBB0_89
	s_barrier

; #define PG8_STAGE(bufoff, gbase, voff) do { _Pragma("unroll") for (int _i = 0; _i < 2; ++_i) \
;         __builtin_amdgcn_global_load_lds((const unsigned*)((const char*)(gbase) + (voff)[_i]), (PG8_LAS unsigned*)(lds + (bufoff) + ldsw + _i * 8192), 16, 0, 0); } while (0)
; #define PG8_LDA(dst, b, h) do { _Pragma("unroll") for (int m = 0; m < 4; ++m) _Pragma("unroll") for (int k = 0; k < 2; ++k) dst[m][k] = *(const PG8_LAS bf16x8*)(lds + PG8_SA(b, h) + aoff + m * 2048 + k * 1024); } while (0)
; #define PG8_LDB(dst, b, h) do { _Pragma("unroll") for (int n = 0; n < 2; ++n) _Pragma("unroll") for (int k = 0; k < 2; ++k) dst[n][k] = *(const PG8_LAS bf16x8*)(lds + PG8_SB(b, h) + boff + n * 2048 + k * 1024); } while (0)
; #define PG8_MMA(ai, bj, At, Bt) do { __builtin_amdgcn_s_setprio(1); _Pragma("unroll") for (int m = 0; m < 4; ++m) _Pragma("unroll") for (int n = 0; n < 2; ++n) _Pragma("unroll") for (int k = 0; k < 2; ++k) \
;         acc[ai][bj][m][n] = __builtin_amdgcn_mfma_f32_16x16x32_bf16(Bt[n][k], At[m][k], acc[ai][bj][m][n], 0, 0, 0); __builtin_amdgcn_s_setprio(0); } while (0)
; #define PG8_WAIT_V(n) asm volatile("s_waitcnt vmcnt(" #n ")" ::: "memory")
; #define PG8_WAIT_L(n) asm volatile("s_waitcnt lgkmcnt(" #n ")" ::: "memory")
; #define PG8_BAR __builtin_amdgcn_s_barrier()
; template <class Epi, class Sched, bool ALIGN_EPI = false, bool SP2 = false>
; __device__ __forceinline__ void gemm_phase(PG8_LAS unsigned char* lds, const Gemm g, const Sched& S, const Epi& E) {
;     ...
;             const char* a1 = cA + (size_t)(t + 1) * kstep;
;             const char* a2 = last ? nA : cA + (size_t)(t + 2) * kstep; const char* b2 = last ? nB : cB + (size_t)(t + 2) * kstep;
;             const char* a3 = a2 + kstep; const char* b3 = b2 + kstep;
;             if (last && has_next) S.a_ready(nxt);
;             if constexpr (SP2) {
;             PG8_LDB(B0, 0, 0); PG8_LDB(B1, 0, 1); PG8_SCHED; PG8_LDA(At, 0, 0); PG8_STAGE(PG8_SA(1, 1), a1 + hstep, voffA);
;             PG8_WAIT_V(8); PG8_WAIT_L(0); PG8_BAR; PG8_MMA(0, 0, At, B0); PG8_MMA(0, 1, At, B1); PG8_BAR; PG8_SCHED;
;             PG8_LDA(At, 0, 1); PG8_STAGE(PG8_SB(0, 0), b2, voffB); PG8_STAGE(PG8_SB(0, 1), b2 + hstep, voffB); PG8_STAGE(PG8_SA(0, 0), a2, voffA);
;             PG8_WAIT_V(8); PG8_WAIT_L(0); PG8_BAR; PG8_MMA(1, 0, At, B0); PG8_MMA(1, 1, At, B1); PG8_BAR; PG8_SCHED;
.LBB0_322:
	s_setprio 1
	s_add_i32 s56, 0, 0x10000
	s_add_i32 vcc_lo, 0, 0x14000
	s_waitcnt lgkmcnt(0)
	ds_read_b128 v[154:157], v246
	ds_read_b128 v[164:167], v246 offset:1024
	ds_read_b128 v[168:171], v246 offset:2048
	ds_read_b128 v[172:175], v246 offset:3072
	ds_read_b128 v[176:179], v246 offset:16384
	ds_read_b128 v[180:183], v246 offset:17408
	ds_read_b128 v[184:187], v246 offset:18432
	ds_read_b128 v[188:191], v246 offset:19456
	s_add_i32 m0, s89, 0xc000
	ds_read_b128 v[192:195], v145
	ds_read_b128 v[196:199], v145 offset:1024
	ds_read_b128 v[222:225], v145 offset:2048
	ds_read_b128 v[226:229], v145 offset:3072
	ds_read_b128 v[230:233], v145 offset:4096
	ds_read_b128 v[234:237], v145 offset:5120
	ds_read_b128 v[238:241], v145 offset:6144
	ds_read_b128 v[242:245], v145 offset:7168
	global_load_lds_dwordx4 v150, s[14:15]
	s_add_i32 m0, s89, 0xe000
	s_nop 0
	global_load_lds_dwordx4 v152, s[14:15]
	s_add_u32 s4, s14, 0xfff80080
	s_addc_u32 s5, s15, -1
	s_cmp_eq_u32 s55, 28
	s_cselect_b32 s53, s1, s5
	s_cselect_b32 s52, s28, s4
	s_cselect_b32 s5, s29, s54
	s_cselect_b32 s4, s43, s45
	s_waitcnt vmcnt(8)
	s_waitcnt lgkmcnt(0)
	s_setprio 0
	s_barrier
	s_waitcnt lgkmcnt(0)
	v_mfma_f32_16x16x32_bf16 v[124:127], v[154:157], v[192:195], v[124:127]
	v_mfma_f32_16x16x32_bf16 v[120:123], v[168:171], v[192:195], v[120:123]
	v_mfma_f32_16x16x32_bf16 v[116:119], v[154:157], v[222:225], v[116:119]
	v_mfma_f32_16x16x32_bf16 v[112:115], v[168:171], v[222:225], v[112:115]
	v_mfma_f32_16x16x32_bf16 v[108:111], v[154:157], v[230:233], v[108:111]
	v_mfma_f32_16x16x32_bf16 v[104:107], v[168:171], v[230:233], v[104:107]
	v_mfma_f32_16x16x32_bf16 v[100:103], v[154:157], v[238:241], v[100:103]
	v_mfma_f32_16x16x32_bf16 v[96:99], v[168:171], v[238:241], v[96:99]
	v_mfma_f32_16x16x32_bf16 v[124:127], v[164:167], v[196:199], v[124:127]
	v_mfma_f32_16x16x32_bf16 v[120:123], v[172:175], v[196:199], v[120:123]
	v_mfma_f32_16x16x32_bf16 v[116:119], v[164:167], v[226:229], v[116:119]
	v_mfma_f32_16x16x32_bf16 v[112:115], v[172:175], v[226:229], v[112:115]
	v_mfma_f32_16x16x32_bf16 v[108:111], v[164:167], v[234:237], v[108:111]
	v_mfma_f32_16x16x32_bf16 v[104:107], v[172:175], v[234:237], v[104:107]
	v_mfma_f32_16x16x32_bf16 v[100:103], v[164:167], v[242:245], v[100:103]
	v_mfma_f32_16x16x32_bf16 v[96:99], v[172:175], v[242:245], v[96:99]
	v_mfma_f32_16x16x32_bf16 v[92:95], v[176:179], v[192:195], v[92:95]
	v_mfma_f32_16x16x32_bf16 v[88:91], v[184:187], v[192:195], v[88:91]
	v_mfma_f32_16x16x32_bf16 v[84:87], v[176:179], v[222:225], v[84:87]
	v_mfma_f32_16x16x32_bf16 v[80:83], v[184:187], v[222:225], v[80:83]
	v_mfma_f32_16x16x32_bf16 v[76:79], v[176:179], v[230:233], v[76:79]
	v_mfma_f32_16x16x32_bf16 v[72:75], v[184:187], v[230:233], v[72:75]
	v_mfma_f32_16x16x32_bf16 v[68:71], v[176:179], v[238:241], v[68:71]
	v_mfma_f32_16x16x32_bf16 v[64:67], v[184:187], v[238:241], v[64:67]
	v_mfma_f32_16x16x32_bf16 v[92:95], v[180:183], v[196:199], v[92:95]
	v_mfma_f32_16x16x32_bf16 v[88:91], v[188:191], v[196:199], v[88:91]
	v_mfma_f32_16x16x32_bf16 v[84:87], v[180:183], v[226:229], v[84:87]
	v_mfma_f32_16x16x32_bf16 v[80:83], v[188:191], v[226:229], v[80:83]
	v_mfma_f32_16x16x32_bf16 v[76:79], v[180:183], v[234:237], v[76:79]
	v_mfma_f32_16x16x32_bf16 v[72:75], v[188:191], v[234:237], v[72:75]
	v_mfma_f32_16x16x32_bf16 v[68:71], v[180:183], v[242:245], v[68:71]
	v_mfma_f32_16x16x32_bf16 v[64:67], v[188:191], v[242:245], v[64:67]
	s_barrier
	s_setprio 1
	s_add_i32 s56, s56, s63
	s_mov_b32 m0, s56
	ds_read_b128 v[192:195], v145 offset:16384
	ds_read_b128 v[196:199], v145 offset:17408
	ds_read_b128 v[222:225], v145 offset:18432
	ds_read_b128 v[226:229], v145 offset:19456
	ds_read_b128 v[230:233], v145 offset:20480
	ds_read_b128 v[234:237], v145 offset:21504
	ds_read_b128 v[238:241], v145 offset:22528
	ds_read_b128 v[242:245], v145 offset:23552
	global_load_lds_dwordx4 v130, s[4:5]
	s_add_i32 m0, s56, 0x2000
	s_add_u32 s56, s4, 0x80000
	s_addc_u32 s57, s5, 0
	s_add_i32 vcc_lo, vcc_lo, s63
	global_load_lds_dwordx4 v134, s[4:5]
	s_mov_b32 m0, vcc_lo
	s_nop 0
	global_load_lds_dwordx4 v130, s[56:57]
	s_add_i32 m0, vcc_lo, 0x2000
	s_nop 0
	global_load_lds_dwordx4 v134, s[56:57]
	s_mov_b32 m0, s89
	s_nop 0
	global_load_lds_dwordx4 v128, s[52:53]
	s_mov_b32 m0, s91
	s_nop 0
	global_load_lds_dwordx4 v132, s[52:53]
	s_add_u32 s98, s52, 0x80
	s_addc_u32 s99, s53, 0
	s_waitcnt vmcnt(8)
	s_waitcnt lgkmcnt(0)
	s_setprio 0
	s_barrier
	s_waitcnt lgkmcnt(0)
	v_mfma_f32_16x16x32_bf16 v[60:63], v[154:157], v[192:195], v[60:63]
	v_mfma_f32_16x16x32_bf16 v[56:59], v[168:171], v[192:195], v[56:59]
	v_mfma_f32_16x16x32_bf16 v[52:55], v[154:157], v[222:225], v[52:55]
	v_mfma_f32_16x16x32_bf16 v[48:51], v[168:171], v[222:225], v[48:51]
	v_mfma_f32_16x16x32_bf16 v[44:47], v[154:157], v[230:233], v[44:47]
	v_mfma_f32_16x16x32_bf16 v[40:43], v[168:171], v[230:233], v[40:43]
	v_mfma_f32_16x16x32_bf16 v[36:39], v[154:157], v[238:241], v[36:39]
	v_mfma_f32_16x16x32_bf16 v[32:35], v[168:171], v[238:241], v[32:35]
	v_mfma_f32_16x16x32_bf16 v[60:63], v[164:167], v[196:199], v[60:63]
	v_mfma_f32_16x16x32_bf16 v[56:59], v[172:175], v[196:199], v[56:59]
	v_mfma_f32_16x16x32_bf16 v[52:55], v[164:167], v[226:229], v[52:55]
	v_mfma_f32_16x16x32_bf16 v[48:51], v[172:175], v[226:229], v[48:51]
	v_mfma_f32_16x16x32_bf16 v[44:47], v[164:167], v[234:237], v[44:47]
	v_mfma_f32_16x16x32_bf16 v[40:43], v[172:175], v[234:237], v[40:43]
	v_mfma_f32_16x16x32_bf16 v[36:39], v[164:167], v[242:245], v[36:39]
	v_mfma_f32_16x16x32_bf16 v[32:35], v[172:175], v[242:245], v[32:35]
	v_mfma_f32_16x16x32_bf16 v[28:31], v[176:179], v[192:195], v[28:31]
	v_mfma_f32_16x16x32_bf16 v[24:27], v[184:187], v[192:195], v[24:27]
	v_mfma_f32_16x16x32_bf16 v[20:23], v[176:179], v[222:225], v[20:23]
	v_mfma_f32_16x16x32_bf16 v[16:19], v[184:187], v[222:225], v[16:19]
	v_mfma_f32_16x16x32_bf16 v[12:15], v[176:179], v[230:233], v[12:15]
	v_mfma_f32_16x16x32_bf16 v[8:11], v[184:187], v[230:233], v[8:11]
	v_mfma_f32_16x16x32_bf16 v[4:7], v[176:179], v[238:241], v[4:7]
	v_mfma_f32_16x16x32_bf16 v[0:3], v[184:187], v[238:241], v[0:3]
	v_mfma_f32_16x16x32_bf16 v[28:31], v[180:183], v[196:199], v[28:31]
	v_mfma_f32_16x16x32_bf16 v[24:27], v[188:191], v[196:199], v[24:27]
	v_mfma_f32_16x16x32_bf16 v[20:23], v[180:183], v[226:229], v[20:23]
	v_mfma_f32_16x16x32_bf16 v[16:19], v[188:191], v[226:229], v[16:19]
	v_mfma_f32_16x16x32_bf16 v[12:15], v[180:183], v[234:237], v[12:15]
	v_mfma_f32_16x16x32_bf16 v[8:11], v[188:191], v[234:237], v[8:11]
	v_mfma_f32_16x16x32_bf16 v[4:7], v[180:183], v[242:245], v[4:7]
	v_mfma_f32_16x16x32_bf16 v[0:3], v[188:191], v[242:245], v[0:3]
	s_barrier
; #define PG8_STAGE(bufoff, gbase, voff) do { _Pragma("unroll") for (int _i = 0; _i < 2; ++_i) \
;         __builtin_amdgcn_global_load_lds((const unsigned*)((const char*)(gbase) + (voff)[_i]), (PG8_LAS unsigned*)(lds + (bufoff) + ldsw + _i * 8192), 16, 0, 0); } while (0)
; #define PG8_LDA(dst, b, h) do { _Pragma("unroll") for (int m = 0; m < 4; ++m) _Pragma("unroll") for (int k = 0; k < 2; ++k) dst[m][k] = *(const PG8_LAS bf16x8*)(lds + PG8_SA(b, h) + aoff + m * 2048 + k * 1024); } while (0)
; #define PG8_LDB(dst, b, h) do { _Pragma("unroll") for (int n = 0; n < 2; ++n) _Pragma("unroll") for (int k = 0; k < 2; ++k) dst[n][k] = *(const PG8_LAS bf16x8*)(lds + PG8_SB(b, h) + boff + n * 2048 + k * 1024); } while (0)
; #define PG8_MMA(ai, bj, At, Bt) do { __builtin_amdgcn_s_setprio(1); _Pragma("unroll") for (int m = 0; m < 4; ++m) _Pragma("unroll") for (int n = 0; n < 2; ++n) _Pragma("unroll") for (int k = 0; k < 2; ++k) \
;         acc[ai][bj][m][n] = __builtin_amdgcn_mfma_f32_16x16x32_bf16(Bt[n][k], At[m][k], acc[ai][bj][m][n], 0, 0, 0); __builtin_amdgcn_s_setprio(0); } while (0)
; #define PG8_WAIT_V(n) asm volatile("s_waitcnt vmcnt(" #n ")" ::: "memory")
; #define PG8_WAIT_L(n) asm volatile("s_waitcnt lgkmcnt(" #n ")" ::: "memory")
; #define PG8_BAR __builtin_amdgcn_s_barrier()
; #define PG8_SCHED __builtin_amdgcn_sched_barrier(0)
; template <class Epi, class Sched, bool ALIGN_EPI = false, bool SP2 = false>
; __device__ __forceinline__ void gemm_phase(PG8_LAS unsigned char* lds, const Gemm g, const Sched& S, const Epi& E) {
;     ...
;             PG8_LDB(B0, 1, 0); PG8_LDB(B1, 1, 1); PG8_SCHED; PG8_LDA(At, 1, 0); PG8_STAGE(PG8_SA(0, 1), a2 + hstep, voffA);
;             PG8_WAIT_V(8); PG8_WAIT_L(0); PG8_BAR; PG8_MMA(0, 0, At, B0); PG8_MMA(0, 1, At, B1); PG8_BAR; PG8_SCHED;
;             PG8_LDA(At, 1, 1); PG8_STAGE(PG8_SB(1, 0), b3, voffB); PG8_STAGE(PG8_SB(1, 1), b3 + hstep, voffB); PG8_STAGE(PG8_SA(1, 0), a3, voffA);
;             PG8_WAIT_V(8); PG8_WAIT_L(0); PG8_BAR; PG8_MMA(1, 0, At, B0); PG8_MMA(1, 1, At, B1); PG8_BAR; PG8_SCHED;
	s_setprio 1
	s_add_i32 s56, 0, 0x18000
	s_add_i32 s57, 0, 0x1c000
	ds_read_b128 v[154:157], v246 offset:32768
	ds_read_b128 v[164:167], v246 offset:33792
	ds_read_b128 v[168:171], v246 offset:34816
	ds_read_b128 v[172:175], v246 offset:35840
	ds_read_b128 v[176:179], v246 offset:49152
	ds_read_b128 v[180:183], v246 offset:50176
	ds_read_b128 v[184:187], v246 offset:51200
	ds_read_b128 v[188:191], v246 offset:52224
	s_add_u32 s52, s52, 0x80000
	s_addc_u32 s53, s53, 0
	s_mov_b32 m0, s12
	ds_read_b128 v[192:195], v145 offset:32768
	ds_read_b128 v[196:199], v145 offset:33792
	ds_read_b128 v[222:225], v145 offset:34816
	ds_read_b128 v[226:229], v145 offset:35840
	ds_read_b128 v[230:233], v145 offset:36864
	ds_read_b128 v[234:237], v145 offset:37888
	ds_read_b128 v[238:241], v145 offset:38912
	ds_read_b128 v[242:245], v145 offset:39936
	global_load_lds_dwordx4 v128, s[52:53]
	s_mov_b32 m0, s13
	s_nop 0
	global_load_lds_dwordx4 v132, s[52:53]
	s_waitcnt vmcnt(8)
	s_waitcnt lgkmcnt(0)
	s_setprio 0
	s_barrier
	s_waitcnt lgkmcnt(0)
	v_mfma_f32_16x16x32_bf16 v[124:127], v[154:157], v[192:195], v[124:127]
	v_mfma_f32_16x16x32_bf16 v[120:123], v[168:171], v[192:195], v[120:123]
	v_mfma_f32_16x16x32_bf16 v[116:119], v[154:157], v[222:225], v[116:119]
	v_mfma_f32_16x16x32_bf16 v[112:115], v[168:171], v[222:225], v[112:115]
	v_mfma_f32_16x16x32_bf16 v[108:111], v[154:157], v[230:233], v[108:111]
	v_mfma_f32_16x16x32_bf16 v[104:107], v[168:171], v[230:233], v[104:107]
	v_mfma_f32_16x16x32_bf16 v[100:103], v[154:157], v[238:241], v[100:103]
	v_mfma_f32_16x16x32_bf16 v[96:99], v[168:171], v[238:241], v[96:99]
	v_mfma_f32_16x16x32_bf16 v[124:127], v[164:167], v[196:199], v[124:127]
	v_mfma_f32_16x16x32_bf16 v[120:123], v[172:175], v[196:199], v[120:123]
	v_mfma_f32_16x16x32_bf16 v[116:119], v[164:167], v[226:229], v[116:119]
	v_mfma_f32_16x16x32_bf16 v[112:115], v[172:175], v[226:229], v[112:115]
	v_mfma_f32_16x16x32_bf16 v[108:111], v[164:167], v[234:237], v[108:111]
	v_mfma_f32_16x16x32_bf16 v[104:107], v[172:175], v[234:237], v[104:107]
	v_mfma_f32_16x16x32_bf16 v[100:103], v[164:167], v[242:245], v[100:103]
	v_mfma_f32_16x16x32_bf16 v[96:99], v[172:175], v[242:245], v[96:99]
	v_mfma_f32_16x16x32_bf16 v[92:95], v[176:179], v[192:195], v[92:95]
	v_mfma_f32_16x16x32_bf16 v[88:91], v[184:187], v[192:195], v[88:91]
	v_mfma_f32_16x16x32_bf16 v[84:87], v[176:179], v[222:225], v[84:87]
	v_mfma_f32_16x16x32_bf16 v[80:83], v[184:187], v[222:225], v[80:83]
	v_mfma_f32_16x16x32_bf16 v[76:79], v[176:179], v[230:233], v[76:79]
	v_mfma_f32_16x16x32_bf16 v[72:75], v[184:187], v[230:233], v[72:75]
	v_mfma_f32_16x16x32_bf16 v[68:71], v[176:179], v[238:241], v[68:71]
	v_mfma_f32_16x16x32_bf16 v[64:67], v[184:187], v[238:241], v[64:67]
	v_mfma_f32_16x16x32_bf16 v[92:95], v[180:183], v[196:199], v[92:95]
	v_mfma_f32_16x16x32_bf16 v[88:91], v[188:191], v[196:199], v[88:91]
	v_mfma_f32_16x16x32_bf16 v[84:87], v[180:183], v[226:229], v[84:87]
	v_mfma_f32_16x16x32_bf16 v[80:83], v[188:191], v[226:229], v[80:83]
	v_mfma_f32_16x16x32_bf16 v[76:79], v[180:183], v[234:237], v[76:79]
	v_mfma_f32_16x16x32_bf16 v[72:75], v[188:191], v[234:237], v[72:75]
	v_mfma_f32_16x16x32_bf16 v[68:71], v[180:183], v[242:245], v[68:71]
	v_mfma_f32_16x16x32_bf16 v[64:67], v[188:191], v[242:245], v[64:67]
	s_barrier
	s_setprio 1
	s_add_i32 s52, s56, s63
	s_mov_b32 m0, s52
	ds_read_b128 v[192:195], v145 offset:49152
	ds_read_b128 v[196:199], v145 offset:50176
	ds_read_b128 v[222:225], v145 offset:51200
	ds_read_b128 v[226:229], v145 offset:52224
	ds_read_b128 v[230:233], v145 offset:53248
	ds_read_b128 v[234:237], v145 offset:54272
	ds_read_b128 v[238:241], v145 offset:55296
	ds_read_b128 v[242:245], v145 offset:56320
	s_add_u32 s4, s4, 0x80
	s_addc_u32 s5, s5, 0
	global_load_lds_dwordx4 v130, s[4:5]
	s_add_i32 m0, s52, 0x2000
	s_add_i32 s52, s57, s63
	global_load_lds_dwordx4 v134, s[4:5]
	s_add_u32 s4, s4, 0x80000
	s_addc_u32 s5, s5, 0
	s_mov_b32 m0, s52
	s_nop 0
	global_load_lds_dwordx4 v130, s[4:5]
	s_add_i32 m0, s52, 0x2000
	s_nop 0
	global_load_lds_dwordx4 v134, s[4:5]
	s_mov_b32 m0, s78
	s_nop 0
	global_load_lds_dwordx4 v128, s[98:99]
	s_mov_b32 m0, s79
	s_nop 0
	global_load_lds_dwordx4 v132, s[98:99]
	s_waitcnt vmcnt(8)
	s_waitcnt lgkmcnt(0)
	s_setprio 0
	s_barrier
	s_waitcnt lgkmcnt(0)
	v_mfma_f32_16x16x32_bf16 v[60:63], v[154:157], v[192:195], v[60:63]
	v_mfma_f32_16x16x32_bf16 v[56:59], v[168:171], v[192:195], v[56:59]
	v_mfma_f32_16x16x32_bf16 v[52:55], v[154:157], v[222:225], v[52:55]
	v_mfma_f32_16x16x32_bf16 v[48:51], v[168:171], v[222:225], v[48:51]
	v_mfma_f32_16x16x32_bf16 v[44:47], v[154:157], v[230:233], v[44:47]
	v_mfma_f32_16x16x32_bf16 v[40:43], v[168:171], v[230:233], v[40:43]
	v_mfma_f32_16x16x32_bf16 v[36:39], v[154:157], v[238:241], v[36:39]
	v_mfma_f32_16x16x32_bf16 v[32:35], v[168:171], v[238:241], v[32:35]
	v_mfma_f32_16x16x32_bf16 v[60:63], v[164:167], v[196:199], v[60:63]
	v_mfma_f32_16x16x32_bf16 v[56:59], v[172:175], v[196:199], v[56:59]
	v_mfma_f32_16x16x32_bf16 v[52:55], v[164:167], v[226:229], v[52:55]
	v_mfma_f32_16x16x32_bf16 v[48:51], v[172:175], v[226:229], v[48:51]
	v_mfma_f32_16x16x32_bf16 v[44:47], v[164:167], v[234:237], v[44:47]
	v_mfma_f32_16x16x32_bf16 v[40:43], v[172:175], v[234:237], v[40:43]
	v_mfma_f32_16x16x32_bf16 v[36:39], v[164:167], v[242:245], v[36:39]
	v_mfma_f32_16x16x32_bf16 v[32:35], v[172:175], v[242:245], v[32:35]
	v_mfma_f32_16x16x32_bf16 v[28:31], v[176:179], v[192:195], v[28:31]
	v_mfma_f32_16x16x32_bf16 v[24:27], v[184:187], v[192:195], v[24:27]
	v_mfma_f32_16x16x32_bf16 v[20:23], v[176:179], v[222:225], v[20:23]
	v_mfma_f32_16x16x32_bf16 v[16:19], v[184:187], v[222:225], v[16:19]
	v_mfma_f32_16x16x32_bf16 v[12:15], v[176:179], v[230:233], v[12:15]
	v_mfma_f32_16x16x32_bf16 v[8:11], v[184:187], v[230:233], v[8:11]
	v_mfma_f32_16x16x32_bf16 v[4:7], v[176:179], v[238:241], v[4:7]
	v_mfma_f32_16x16x32_bf16 v[0:3], v[184:187], v[238:241], v[0:3]
	v_mfma_f32_16x16x32_bf16 v[28:31], v[180:183], v[196:199], v[28:31]
	v_mfma_f32_16x16x32_bf16 v[24:27], v[188:191], v[196:199], v[24:27]
	v_mfma_f32_16x16x32_bf16 v[20:23], v[180:183], v[226:229], v[20:23]
	v_mfma_f32_16x16x32_bf16 v[16:19], v[188:191], v[226:229], v[16:19]
	v_mfma_f32_16x16x32_bf16 v[12:15], v[180:183], v[234:237], v[12:15]
	v_mfma_f32_16x16x32_bf16 v[8:11], v[188:191], v[234:237], v[8:11]
	v_mfma_f32_16x16x32_bf16 v[4:7], v[180:183], v[242:245], v[4:7]
	v_mfma_f32_16x16x32_bf16 v[0:3], v[188:191], v[242:245], v[0:3]
	s_barrier
	s_add_i32 s55, s55, 2
	s_add_u32 s14, s14, 0x100
	s_addc_u32 s15, s15, 0
	s_add_u32 s45, s45, 0x100
	s_addc_u32 s54, s54, 0
	s_cmp_gt_u32 s55, 29
	s_cbranch_scc0 .LBB0_322
	s_and_b64 vcc, exec, s[82:83]
	s_cbranch_vccz .LBB0_325
	s_barrier

; #define PG8_STAGE(bufoff, gbase, voff) do { _Pragma("unroll") for (int _i = 0; _i < 2; ++_i) \
;         __builtin_amdgcn_global_load_lds((const unsigned*)((const char*)(gbase) + (voff)[_i]), (PG8_LAS unsigned*)(lds + (bufoff) + ldsw + _i * 8192), 16, 0, 0); } while (0)
; #define PG8_LDA(dst, b, h) do { _Pragma("unroll") for (int m = 0; m < 4; ++m) _Pragma("unroll") for (int k = 0; k < 2; ++k) dst[m][k] = *(const PG8_LAS bf16x8*)(lds + PG8_SA(b, h) + aoff + m * 2048 + k * 1024); } while (0)
; #define PG8_LDB(dst, b, h) do { _Pragma("unroll") for (int n = 0; n < 2; ++n) _Pragma("unroll") for (int k = 0; k < 2; ++k) dst[n][k] = *(const PG8_LAS bf16x8*)(lds + PG8_SB(b, h) + boff + n * 2048 + k * 1024); } while (0)
; #define PG8_MMA(ai, bj, At, Bt) do { __builtin_amdgcn_s_setprio(1); _Pragma("unroll") for (int m = 0; m < 4; ++m) _Pragma("unroll") for (int n = 0; n < 2; ++n) _Pragma("unroll") for (int k = 0; k < 2; ++k) \
;         acc[ai][bj][m][n] = __builtin_amdgcn_mfma_f32_16x16x32_bf16(Bt[n][k], At[m][k], acc[ai][bj][m][n], 0, 0, 0); __builtin_amdgcn_s_setprio(0); } while (0)
; #define PG8_WAIT_V(n) asm volatile("s_waitcnt vmcnt(" #n ")" ::: "memory")
; #define PG8_WAIT_L(n) asm volatile("s_waitcnt lgkmcnt(" #n ")" ::: "memory")
; #define PG8_BAR __builtin_amdgcn_s_barrier()
; template <class Epi, class Sched, bool ALIGN_EPI = false, bool SP2 = false>
; __device__ __forceinline__ void gemm_phase(PG8_LAS unsigned char* lds, const Gemm g, const Sched& S, const Epi& E) {
;     ...
;             const char* a1 = cA + (size_t)(t + 1) * kstep;
;             const char* a2 = last ? nA : cA + (size_t)(t + 2) * kstep; const char* b2 = last ? nB : cB + (size_t)(t + 2) * kstep;
;             const char* a3 = a2 + kstep; const char* b3 = b2 + kstep;
;             if (last && has_next) S.a_ready(nxt);
;             if constexpr (SP2) {
;             PG8_LDB(B0, 0, 0); PG8_LDB(B1, 0, 1); PG8_SCHED; PG8_LDA(At, 0, 0); PG8_STAGE(PG8_SA(1, 1), a1 + hstep, voffA);
;             PG8_WAIT_V(8); PG8_WAIT_L(0); PG8_BAR; PG8_MMA(0, 0, At, B0); PG8_MMA(0, 1, At, B1); PG8_BAR; PG8_SCHED;
;             PG8_LDA(At, 0, 1); PG8_STAGE(PG8_SB(0, 0), b2, voffB); PG8_STAGE(PG8_SB(0, 1), b2 + hstep, voffB); PG8_STAGE(PG8_SA(0, 0), a2, voffA);
;             PG8_WAIT_V(8); PG8_WAIT_L(0); PG8_BAR; PG8_MMA(1, 0, At, B0); PG8_MMA(1, 1, At, B1); PG8_BAR; PG8_SCHED;
.LBB0_849:
	s_setprio 1
	s_add_i32 s76, 0, 0x10000
	s_add_i32 s78, 0, 0x14000
	ds_read_b128 v[144:147], v200
	ds_read_b128 v[148:151], v200 offset:1024
	ds_read_b128 v[152:155], v200 offset:2048
	ds_read_b128 v[156:159], v200 offset:3072
	ds_read_b128 v[164:167], v200 offset:16384
	ds_read_b128 v[168:171], v200 offset:17408
	ds_read_b128 v[172:175], v200 offset:18432
	ds_read_b128 v[176:179], v200 offset:19456
	s_add_i32 m0, s51, 0xc000
	ds_read_b128 v[180:183], v143
	ds_read_b128 v[184:187], v143 offset:1024
	ds_read_b128 v[188:191], v143 offset:2048
	ds_read_b128 v[192:195], v143 offset:3072
	ds_read_b128 v[196:199], v143 offset:4096
	ds_read_b128 v[222:225], v143 offset:5120
	ds_read_b128 v[226:229], v143 offset:6144
	ds_read_b128 v[230:233], v143 offset:7168
	global_load_lds_dwordx4 v134, s[70:71]
	s_add_i32 m0, s51, 0xe000
	s_nop 0
	global_load_lds_dwordx4 v136, s[70:71]
	s_add_u32 s4, s70, 0xfff80080
	s_addc_u32 s5, s71, -1
	s_cmp_eq_u32 s75, 28
	s_cselect_b32 s53, s11, s5
	s_cselect_b32 s52, s63, s4
	s_cselect_b32 s5, s13, s74
	s_cselect_b32 s4, s72, s73
	s_waitcnt vmcnt(8)
	s_waitcnt lgkmcnt(0)
	s_setprio 0
	s_barrier
	s_waitcnt lgkmcnt(0)
	v_mfma_f32_16x16x32_bf16 v[124:127], v[144:147], v[180:183], v[124:127]
	v_mfma_f32_16x16x32_bf16 v[116:119], v[152:155], v[180:183], v[116:119]
	v_mfma_f32_16x16x32_bf16 v[108:111], v[144:147], v[188:191], v[108:111]
	v_mfma_f32_16x16x32_bf16 v[100:103], v[152:155], v[188:191], v[100:103]
	v_mfma_f32_16x16x32_bf16 v[92:95], v[144:147], v[196:199], v[92:95]
	v_mfma_f32_16x16x32_bf16 v[84:87], v[152:155], v[196:199], v[84:87]
	v_mfma_f32_16x16x32_bf16 v[76:79], v[144:147], v[226:229], v[76:79]
	v_mfma_f32_16x16x32_bf16 v[68:71], v[152:155], v[226:229], v[68:71]
	v_mfma_f32_16x16x32_bf16 v[124:127], v[148:151], v[184:187], v[124:127]
	v_mfma_f32_16x16x32_bf16 v[116:119], v[156:159], v[184:187], v[116:119]
	v_mfma_f32_16x16x32_bf16 v[108:111], v[148:151], v[192:195], v[108:111]
	v_mfma_f32_16x16x32_bf16 v[100:103], v[156:159], v[192:195], v[100:103]
	v_mfma_f32_16x16x32_bf16 v[92:95], v[148:151], v[222:225], v[92:95]
	v_mfma_f32_16x16x32_bf16 v[84:87], v[156:159], v[222:225], v[84:87]
	v_mfma_f32_16x16x32_bf16 v[76:79], v[148:151], v[230:233], v[76:79]
	v_mfma_f32_16x16x32_bf16 v[68:71], v[156:159], v[230:233], v[68:71]
	v_mfma_f32_16x16x32_bf16 v[120:123], v[164:167], v[180:183], v[120:123]
	v_mfma_f32_16x16x32_bf16 v[112:115], v[172:175], v[180:183], v[112:115]
	v_mfma_f32_16x16x32_bf16 v[104:107], v[164:167], v[188:191], v[104:107]
	v_mfma_f32_16x16x32_bf16 v[96:99], v[172:175], v[188:191], v[96:99]
	v_mfma_f32_16x16x32_bf16 v[88:91], v[164:167], v[196:199], v[88:91]
	v_mfma_f32_16x16x32_bf16 v[80:83], v[172:175], v[196:199], v[80:83]
	v_mfma_f32_16x16x32_bf16 v[72:75], v[164:167], v[226:229], v[72:75]
	v_mfma_f32_16x16x32_bf16 v[64:67], v[172:175], v[226:229], v[64:67]
	v_mfma_f32_16x16x32_bf16 v[120:123], v[168:171], v[184:187], v[120:123]
	v_mfma_f32_16x16x32_bf16 v[112:115], v[176:179], v[184:187], v[112:115]
	v_mfma_f32_16x16x32_bf16 v[104:107], v[168:171], v[192:195], v[104:107]
	v_mfma_f32_16x16x32_bf16 v[96:99], v[176:179], v[192:195], v[96:99]
	v_mfma_f32_16x16x32_bf16 v[88:91], v[168:171], v[222:225], v[88:91]
	v_mfma_f32_16x16x32_bf16 v[80:83], v[176:179], v[222:225], v[80:83]
	v_mfma_f32_16x16x32_bf16 v[72:75], v[168:171], v[230:233], v[72:75]
	v_mfma_f32_16x16x32_bf16 v[64:67], v[176:179], v[230:233], v[64:67]
	s_barrier
	s_setprio 1
	s_add_i32 s76, s76, s24
	s_mov_b32 m0, s76
	ds_read_b128 v[180:183], v143 offset:16384
	ds_read_b128 v[184:187], v143 offset:17408
	ds_read_b128 v[188:191], v143 offset:18432
	ds_read_b128 v[192:195], v143 offset:19456
	ds_read_b128 v[196:199], v143 offset:20480
	ds_read_b128 v[222:225], v143 offset:21504
	ds_read_b128 v[226:229], v143 offset:22528
	ds_read_b128 v[230:233], v143 offset:23552
	global_load_lds_dwordx4 v160, s[4:5]
	s_add_i32 m0, s76, 0x2000
	s_add_u32 s76, s4, 0x80000
	s_addc_u32 s77, s5, 0
	s_add_i32 s78, s78, s24
	global_load_lds_dwordx4 v128, s[4:5]
	s_mov_b32 m0, s78
	s_nop 0
	global_load_lds_dwordx4 v160, s[76:77]
	s_add_i32 m0, s78, 0x2000
	s_nop 0
	global_load_lds_dwordx4 v128, s[76:77]
	s_mov_b32 m0, s51
	s_nop 0
	global_load_lds_dwordx4 v132, s[52:53]
	s_mov_b32 m0, s55
	s_nop 0
	global_load_lds_dwordx4 v130, s[52:53]
	s_add_u32 s98, s52, 0x80
	s_addc_u32 s99, s53, 0
	s_waitcnt vmcnt(8)
	s_waitcnt lgkmcnt(0)
	s_setprio 0
	s_barrier
	s_waitcnt lgkmcnt(0)
	v_mfma_f32_16x16x32_bf16 v[60:63], v[144:147], v[180:183], v[60:63]
	v_mfma_f32_16x16x32_bf16 v[52:55], v[152:155], v[180:183], v[52:55]
	v_mfma_f32_16x16x32_bf16 v[44:47], v[144:147], v[188:191], v[44:47]
	v_mfma_f32_16x16x32_bf16 v[36:39], v[152:155], v[188:191], v[36:39]
	v_mfma_f32_16x16x32_bf16 v[28:31], v[144:147], v[196:199], v[28:31]
	v_mfma_f32_16x16x32_bf16 v[20:23], v[152:155], v[196:199], v[20:23]
	v_mfma_f32_16x16x32_bf16 v[12:15], v[144:147], v[226:229], v[12:15]
	v_mfma_f32_16x16x32_bf16 v[4:7], v[152:155], v[226:229], v[4:7]
	v_mfma_f32_16x16x32_bf16 v[60:63], v[148:151], v[184:187], v[60:63]
	v_mfma_f32_16x16x32_bf16 v[52:55], v[156:159], v[184:187], v[52:55]
	v_mfma_f32_16x16x32_bf16 v[44:47], v[148:151], v[192:195], v[44:47]
	v_mfma_f32_16x16x32_bf16 v[36:39], v[156:159], v[192:195], v[36:39]
	v_mfma_f32_16x16x32_bf16 v[28:31], v[148:151], v[222:225], v[28:31]
	v_mfma_f32_16x16x32_bf16 v[20:23], v[156:159], v[222:225], v[20:23]
	v_mfma_f32_16x16x32_bf16 v[12:15], v[148:151], v[230:233], v[12:15]
	v_mfma_f32_16x16x32_bf16 v[4:7], v[156:159], v[230:233], v[4:7]
	v_mfma_f32_16x16x32_bf16 v[56:59], v[164:167], v[180:183], v[56:59]
	v_mfma_f32_16x16x32_bf16 v[48:51], v[172:175], v[180:183], v[48:51]
	v_mfma_f32_16x16x32_bf16 v[40:43], v[164:167], v[188:191], v[40:43]
	v_mfma_f32_16x16x32_bf16 v[32:35], v[172:175], v[188:191], v[32:35]
	v_mfma_f32_16x16x32_bf16 v[24:27], v[164:167], v[196:199], v[24:27]
	v_mfma_f32_16x16x32_bf16 v[16:19], v[172:175], v[196:199], v[16:19]
	v_mfma_f32_16x16x32_bf16 v[8:11], v[164:167], v[226:229], v[8:11]
	v_mfma_f32_16x16x32_bf16 v[0:3], v[172:175], v[226:229], v[0:3]
	v_mfma_f32_16x16x32_bf16 v[56:59], v[168:171], v[184:187], v[56:59]
	v_mfma_f32_16x16x32_bf16 v[48:51], v[176:179], v[184:187], v[48:51]
	v_mfma_f32_16x16x32_bf16 v[40:43], v[168:171], v[192:195], v[40:43]
	v_mfma_f32_16x16x32_bf16 v[32:35], v[176:179], v[192:195], v[32:35]
	v_mfma_f32_16x16x32_bf16 v[24:27], v[168:171], v[222:225], v[24:27]
	v_mfma_f32_16x16x32_bf16 v[16:19], v[176:179], v[222:225], v[16:19]
	v_mfma_f32_16x16x32_bf16 v[8:11], v[168:171], v[230:233], v[8:11]
	v_mfma_f32_16x16x32_bf16 v[0:3], v[176:179], v[230:233], v[0:3]
	s_barrier
; #define PG8_STAGE(bufoff, gbase, voff) do { _Pragma("unroll") for (int _i = 0; _i < 2; ++_i) \
;         __builtin_amdgcn_global_load_lds((const unsigned*)((const char*)(gbase) + (voff)[_i]), (PG8_LAS unsigned*)(lds + (bufoff) + ldsw + _i * 8192), 16, 0, 0); } while (0)
; #define PG8_LDA(dst, b, h) do { _Pragma("unroll") for (int m = 0; m < 4; ++m) _Pragma("unroll") for (int k = 0; k < 2; ++k) dst[m][k] = *(const PG8_LAS bf16x8*)(lds + PG8_SA(b, h) + aoff + m * 2048 + k * 1024); } while (0)
; #define PG8_LDB(dst, b, h) do { _Pragma("unroll") for (int n = 0; n < 2; ++n) _Pragma("unroll") for (int k = 0; k < 2; ++k) dst[n][k] = *(const PG8_LAS bf16x8*)(lds + PG8_SB(b, h) + boff + n * 2048 + k * 1024); } while (0)
; #define PG8_MMA(ai, bj, At, Bt) do { __builtin_amdgcn_s_setprio(1); _Pragma("unroll") for (int m = 0; m < 4; ++m) _Pragma("unroll") for (int n = 0; n < 2; ++n) _Pragma("unroll") for (int k = 0; k < 2; ++k) \
;         acc[ai][bj][m][n] = __builtin_amdgcn_mfma_f32_16x16x32_bf16(Bt[n][k], At[m][k], acc[ai][bj][m][n], 0, 0, 0); __builtin_amdgcn_s_setprio(0); } while (0)
; #define PG8_WAIT_V(n) asm volatile("s_waitcnt vmcnt(" #n ")" ::: "memory")
; #define PG8_WAIT_L(n) asm volatile("s_waitcnt lgkmcnt(" #n ")" ::: "memory")
; #define PG8_BAR __builtin_amdgcn_s_barrier()
; #define PG8_SCHED __builtin_amdgcn_sched_barrier(0)
; template <class Epi, class Sched, bool ALIGN_EPI = false, bool SP2 = false>
; __device__ __forceinline__ void gemm_phase(PG8_LAS unsigned char* lds, const Gemm g, const Sched& S, const Epi& E) {
;     ...
;             PG8_LDB(B0, 1, 0); PG8_LDB(B1, 1, 1); PG8_SCHED; PG8_LDA(At, 1, 0); PG8_STAGE(PG8_SA(0, 1), a2 + hstep, voffA);
;             PG8_WAIT_V(8); PG8_WAIT_L(0); PG8_BAR; PG8_MMA(0, 0, At, B0); PG8_MMA(0, 1, At, B1); PG8_BAR; PG8_SCHED;
;             PG8_LDA(At, 1, 1); PG8_STAGE(PG8_SB(1, 0), b3, voffB); PG8_STAGE(PG8_SB(1, 1), b3 + hstep, voffB); PG8_STAGE(PG8_SA(1, 0), a3, voffA);
;             PG8_WAIT_V(8); PG8_WAIT_L(0); PG8_BAR; PG8_MMA(1, 0, At, B0); PG8_MMA(1, 1, At, B1); PG8_BAR; PG8_SCHED;
	s_setprio 1
	s_add_i32 s76, 0, 0x18000
	s_add_i32 s77, 0, 0x1c000
	ds_read_b128 v[144:147], v200 offset:32768
	ds_read_b128 v[148:151], v200 offset:33792
	ds_read_b128 v[152:155], v200 offset:34816
	ds_read_b128 v[156:159], v200 offset:35840
	ds_read_b128 v[164:167], v200 offset:49152
	ds_read_b128 v[168:171], v200 offset:50176
	ds_read_b128 v[172:175], v200 offset:51200
	ds_read_b128 v[176:179], v200 offset:52224
	s_add_u32 s52, s52, 0x80000
	s_addc_u32 s53, s53, 0
	s_mov_b32 m0, s56
	ds_read_b128 v[180:183], v143 offset:32768
	ds_read_b128 v[184:187], v143 offset:33792
	ds_read_b128 v[188:191], v143 offset:34816
	ds_read_b128 v[192:195], v143 offset:35840
	ds_read_b128 v[196:199], v143 offset:36864
	ds_read_b128 v[222:225], v143 offset:37888
	ds_read_b128 v[226:229], v143 offset:38912
	ds_read_b128 v[230:233], v143 offset:39936
	global_load_lds_dwordx4 v132, s[52:53]
	s_mov_b32 m0, s57
	s_nop 0
	global_load_lds_dwordx4 v130, s[52:53]
	s_waitcnt vmcnt(8)
	s_waitcnt lgkmcnt(0)
	s_setprio 0
	s_barrier
	s_waitcnt lgkmcnt(0)
	v_mfma_f32_16x16x32_bf16 v[124:127], v[144:147], v[180:183], v[124:127]
	v_mfma_f32_16x16x32_bf16 v[116:119], v[152:155], v[180:183], v[116:119]
	v_mfma_f32_16x16x32_bf16 v[108:111], v[144:147], v[188:191], v[108:111]
	v_mfma_f32_16x16x32_bf16 v[100:103], v[152:155], v[188:191], v[100:103]
	v_mfma_f32_16x16x32_bf16 v[92:95], v[144:147], v[196:199], v[92:95]
	v_mfma_f32_16x16x32_bf16 v[84:87], v[152:155], v[196:199], v[84:87]
	v_mfma_f32_16x16x32_bf16 v[76:79], v[144:147], v[226:229], v[76:79]
	v_mfma_f32_16x16x32_bf16 v[68:71], v[152:155], v[226:229], v[68:71]
	v_mfma_f32_16x16x32_bf16 v[124:127], v[148:151], v[184:187], v[124:127]
	v_mfma_f32_16x16x32_bf16 v[116:119], v[156:159], v[184:187], v[116:119]
	v_mfma_f32_16x16x32_bf16 v[108:111], v[148:151], v[192:195], v[108:111]
	v_mfma_f32_16x16x32_bf16 v[100:103], v[156:159], v[192:195], v[100:103]
	v_mfma_f32_16x16x32_bf16 v[92:95], v[148:151], v[222:225], v[92:95]
	v_mfma_f32_16x16x32_bf16 v[84:87], v[156:159], v[222:225], v[84:87]
	v_mfma_f32_16x16x32_bf16 v[76:79], v[148:151], v[230:233], v[76:79]
	v_mfma_f32_16x16x32_bf16 v[68:71], v[156:159], v[230:233], v[68:71]
	v_mfma_f32_16x16x32_bf16 v[120:123], v[164:167], v[180:183], v[120:123]
	v_mfma_f32_16x16x32_bf16 v[112:115], v[172:175], v[180:183], v[112:115]
	v_mfma_f32_16x16x32_bf16 v[104:107], v[164:167], v[188:191], v[104:107]
	v_mfma_f32_16x16x32_bf16 v[96:99], v[172:175], v[188:191], v[96:99]
	v_mfma_f32_16x16x32_bf16 v[88:91], v[164:167], v[196:199], v[88:91]
	v_mfma_f32_16x16x32_bf16 v[80:83], v[172:175], v[196:199], v[80:83]
	v_mfma_f32_16x16x32_bf16 v[72:75], v[164:167], v[226:229], v[72:75]
	v_mfma_f32_16x16x32_bf16 v[64:67], v[172:175], v[226:229], v[64:67]
	v_mfma_f32_16x16x32_bf16 v[120:123], v[168:171], v[184:187], v[120:123]
	v_mfma_f32_16x16x32_bf16 v[112:115], v[176:179], v[184:187], v[112:115]
	v_mfma_f32_16x16x32_bf16 v[104:107], v[168:171], v[192:195], v[104:107]
	v_mfma_f32_16x16x32_bf16 v[96:99], v[176:179], v[192:195], v[96:99]
	v_mfma_f32_16x16x32_bf16 v[88:91], v[168:171], v[222:225], v[88:91]
	v_mfma_f32_16x16x32_bf16 v[80:83], v[176:179], v[222:225], v[80:83]
	v_mfma_f32_16x16x32_bf16 v[72:75], v[168:171], v[230:233], v[72:75]
	v_mfma_f32_16x16x32_bf16 v[64:67], v[176:179], v[230:233], v[64:67]
	s_barrier
	s_setprio 1
	s_add_i32 s52, s76, s24
	s_mov_b32 m0, s52
	ds_read_b128 v[180:183], v143 offset:49152
	ds_read_b128 v[184:187], v143 offset:50176
	ds_read_b128 v[188:191], v143 offset:51200
	ds_read_b128 v[192:195], v143 offset:52224
	ds_read_b128 v[196:199], v143 offset:53248
	ds_read_b128 v[222:225], v143 offset:54272
	ds_read_b128 v[226:229], v143 offset:55296
	ds_read_b128 v[230:233], v143 offset:56320
	s_add_u32 s4, s4, 0x80
	s_addc_u32 s5, s5, 0
	global_load_lds_dwordx4 v160, s[4:5]
	s_add_i32 m0, s52, 0x2000
	s_add_i32 s52, s77, s24
	global_load_lds_dwordx4 v128, s[4:5]
	s_add_u32 s4, s4, 0x80000
	s_addc_u32 s5, s5, 0
	s_mov_b32 m0, s52
	s_nop 0
	global_load_lds_dwordx4 v160, s[4:5]
	s_add_i32 m0, s52, 0x2000
	s_nop 0
	global_load_lds_dwordx4 v128, s[4:5]
	s_mov_b32 m0, s58
	s_nop 0
	global_load_lds_dwordx4 v132, s[98:99]
	s_mov_b32 m0, s59
	s_nop 0
	global_load_lds_dwordx4 v130, s[98:99]
	s_waitcnt vmcnt(8)
	s_waitcnt lgkmcnt(0)
	s_setprio 0
	s_barrier
	s_waitcnt lgkmcnt(0)
	v_mfma_f32_16x16x32_bf16 v[60:63], v[144:147], v[180:183], v[60:63]
	v_mfma_f32_16x16x32_bf16 v[52:55], v[152:155], v[180:183], v[52:55]
	v_mfma_f32_16x16x32_bf16 v[44:47], v[144:147], v[188:191], v[44:47]
	v_mfma_f32_16x16x32_bf16 v[36:39], v[152:155], v[188:191], v[36:39]
	v_mfma_f32_16x16x32_bf16 v[28:31], v[144:147], v[196:199], v[28:31]
	v_mfma_f32_16x16x32_bf16 v[20:23], v[152:155], v[196:199], v[20:23]
	v_mfma_f32_16x16x32_bf16 v[12:15], v[144:147], v[226:229], v[12:15]
	v_mfma_f32_16x16x32_bf16 v[4:7], v[152:155], v[226:229], v[4:7]
	v_mfma_f32_16x16x32_bf16 v[60:63], v[148:151], v[184:187], v[60:63]
	v_mfma_f32_16x16x32_bf16 v[52:55], v[156:159], v[184:187], v[52:55]
	v_mfma_f32_16x16x32_bf16 v[44:47], v[148:151], v[192:195], v[44:47]
	v_mfma_f32_16x16x32_bf16 v[36:39], v[156:159], v[192:195], v[36:39]
	v_mfma_f32_16x16x32_bf16 v[28:31], v[148:151], v[222:225], v[28:31]
	v_mfma_f32_16x16x32_bf16 v[20:23], v[156:159], v[222:225], v[20:23]
	v_mfma_f32_16x16x32_bf16 v[12:15], v[148:151], v[230:233], v[12:15]
	v_mfma_f32_16x16x32_bf16 v[4:7], v[156:159], v[230:233], v[4:7]
	v_mfma_f32_16x16x32_bf16 v[56:59], v[164:167], v[180:183], v[56:59]
	v_mfma_f32_16x16x32_bf16 v[48:51], v[172:175], v[180:183], v[48:51]
	v_mfma_f32_16x16x32_bf16 v[40:43], v[164:167], v[188:191], v[40:43]
	v_mfma_f32_16x16x32_bf16 v[32:35], v[172:175], v[188:191], v[32:35]
	v_mfma_f32_16x16x32_bf16 v[24:27], v[164:167], v[196:199], v[24:27]
	v_mfma_f32_16x16x32_bf16 v[16:19], v[172:175], v[196:199], v[16:19]
	v_mfma_f32_16x16x32_bf16 v[8:11], v[164:167], v[226:229], v[8:11]
	v_mfma_f32_16x16x32_bf16 v[0:3], v[172:175], v[226:229], v[0:3]
	v_mfma_f32_16x16x32_bf16 v[56:59], v[168:171], v[184:187], v[56:59]
	v_mfma_f32_16x16x32_bf16 v[48:51], v[176:179], v[184:187], v[48:51]
	v_mfma_f32_16x16x32_bf16 v[40:43], v[168:171], v[192:195], v[40:43]
	v_mfma_f32_16x16x32_bf16 v[32:35], v[176:179], v[192:195], v[32:35]
	v_mfma_f32_16x16x32_bf16 v[24:27], v[168:171], v[222:225], v[24:27]
	v_mfma_f32_16x16x32_bf16 v[16:19], v[176:179], v[222:225], v[16:19]
	v_mfma_f32_16x16x32_bf16 v[8:11], v[168:171], v[230:233], v[8:11]
	v_mfma_f32_16x16x32_bf16 v[0:3], v[176:179], v[230:233], v[0:3]
	s_barrier
	s_add_i32 s75, s75, 2
	s_add_u32 s70, s70, 0x100
	s_addc_u32 s71, s71, 0
	s_add_u32 s73, s73, 0x100
	s_addc_u32 s74, s74, 0
	s_cmp_gt_u32 s75, 29
	s_cbranch_scc0 .LBB0_849
	s_and_b64 vcc, exec, s[8:9]
	s_cbranch_vccz .LBB0_852
	s_barrier
